# GEMM tile transition: lagging wave group runs its epilogue before its final post-MMA barrier so both groups' epilogues overlap (on top of trim+defer)
# baseline (speedup 1.0000x reference)
; #define PG8_STAGE(bufoff, gbase, voff) do { _Pragma("unroll") for (int _i = 0; _i < 2; ++_i) \
;         __builtin_amdgcn_global_load_lds((const unsigned*)((const char*)(gbase) + (voff)[_i]), (LAS unsigned*)(lds + (bufoff) + ldsw + _i * 8192), 16, 0, 0); } while (0)
; #define PG8_WAIT_V(n) asm volatile("s_waitcnt vmcnt(" #n ")" ::: "memory")
; #define PG8_BAR __builtin_amdgcn_s_barrier()
; #define tid fresh_tid(wave_s)
; template <class Epi, class Sched>
; __device__ __forceinline__ void gemm_phase(LAS unsigned char* lds, const Gemm g, const Sched& S, const Epi& E, int tid) {
;     ...
;     for (int i = 0; i < 2; ++i) { int R, C; stage_rc(tid * 16 + i * 8192, R, C); const int Rb = Epi::PERM ? ((R & ~31) + perm32(R & 31)) : R;
;         voffA[i] = (unsigned)(R * K + C) * 2u; voffB[i] = (unsigned)(Rb * K + C) * 2u; }
;     ...
;     const char* cA = (const char*)g.A + (size_t)cur.pm * tstep; const char* cB = (const char*)g.Bt + (size_t)cur.pn * tstep;
;     PG8_STAGE(PG8_SB(0, 0), cB, voffB); PG8_STAGE(PG8_SA(0, 0), cA, voffA); PG8_STAGE(PG8_SB(0, 1), cB + hstep, voffB); PG8_STAGE(PG8_SA(0, 1), cA + hstep, voffA);
;     if (wr == 1) PG8_BAR;
;     PG8_WAIT_V(4); PG8_BAR;
;     PG8_STAGE(PG8_SB(1, 0), cB + kstep, voffB); PG8_STAGE(PG8_SA(1, 0), cA + kstep, voffA); PG8_STAGE(PG8_SB(1, 1), cB + hstep + kstep, voffB);
;     PG8_WAIT_V(6); PG8_BAR;
.LBB0_86:
	v_bfe_i32 v2, v12, 27, 1
	v_lshlrev_b32_e32 v0, 4, v12
	v_lshrrev_b32_e32 v2, 22, v2
	v_add_u32_e32 v2, v0, v2
	v_and_b32_e32 v2, 0xfffffc00, v2
	v_ashrrev_i32_e32 v1, 31, v12
	v_sub_u32_e32 v2, v0, v2
	v_lshrrev_b32_e32 v1, 26, v1
	v_lshrrev_b32_e32 v3, 4, v2
	v_add_u32_e32 v1, v12, v1
	v_bitop3_b32 v3, v3, v2, 32 bitop3:0x6c
	v_ashrrev_i32_e32 v2, 31, v2
	v_ashrrev_i32_e32 v1, 6, v1
	v_lshrrev_b32_e32 v2, 26, v2
	v_lshlrev_b32_e32 v4, 3, v1
	v_add_u32_e32 v2, v3, v2
	v_and_b32_e32 v4, -16, v4
	v_ashrrev_i32_e32 v2, 6, v2
	v_lshlrev_b32_e32 v1, 5, v1
	v_add_u32_e32 v4, v2, v4
	v_and_b32_e32 v13, 32, v1
	v_mul_i32_i24_e32 v1, 64, v2
	v_sub_u32_e32 v1, v3, v1
	v_lshlrev_b32_e32 v3, 1, v4
	v_lshrrev_b32_e32 v5, 2, v4
	v_and_b32_e32 v2, 3, v2
	v_ashrrev_i16_sdwa v1, v178, sext(v1) dst_sel:DWORD dst_unused:UNUSED_PAD src0_sel:DWORD src1_sel:BYTE_0
	v_and_b32_e32 v3, 24, v3
	v_and_b32_e32 v5, 4, v5
	v_and_or_b32 v2, v4, s2, v2
	v_bfe_i32 v14, v1, 0, 16
	v_or3_b32 v2, v2, v5, v3
	v_add_u32_e32 v1, v13, v14
	v_mul_lo_u32 v15, v4, s0
	v_mul_lo_u32 v2, v2, s0
	v_add_u32_e32 v0, 0x2000, v0
	v_add_lshl_u32 v128, v1, v15, 1
	v_add_lshl_u32 v154, v2, v1, 1
	v_ashrrev_i32_e32 v1, 31, v0
	v_lshrrev_b32_e32 v1, 22, v1
	v_add_u32_e32 v1, v0, v1
	v_ashrrev_i32_e32 v1, 10, v1
	v_mul_i32_i24_e32 v2, 0x400, v1
	v_sub_u32_e32 v0, v0, v2
	v_lshrrev_b32_e32 v2, 4, v0
	v_bitop3_b32 v0, v2, v0, 32 bitop3:0x6c
	v_ashrrev_i32_e32 v3, 31, v0
	v_lshrrev_b32_e32 v3, 26, v3
	v_lshlrev_b32_e32 v2, 3, v1
	v_add_u32_e32 v3, v0, v3
	v_and_b32_e32 v2, -16, v2
	v_ashrrev_i32_e32 v4, 6, v3
	v_lshlrev_b32_e32 v1, 5, v1
	v_add_u32_e32 v2, v4, v2
	v_and_b32_e32 v16, 32, v1
	v_and_b32_e32 v1, 0xc0, v3
	v_sub_u32_e32 v0, v0, v1
	v_lshlrev_b32_e32 v1, 1, v2
	v_lshrrev_b32_e32 v3, 2, v2
	v_and_b32_e32 v4, 3, v4
	v_ashrrev_i16_sdwa v0, v178, sext(v0) dst_sel:DWORD dst_unused:UNUSED_PAD src0_sel:DWORD src1_sel:BYTE_0
	v_and_b32_e32 v1, 24, v1
	v_and_b32_e32 v3, 4, v3
	v_and_or_b32 v4, v2, s2, v4
	v_bfe_i32 v17, v0, 0, 16
	v_or3_b32 v1, v4, v3, v1
	s_lshr_b32 s82, s74, 5
	v_add_u32_e32 v0, v16, v17
	v_mul_lo_u32 v18, v2, s0
	v_mul_lo_u32 v1, v1, s0
	s_abs_i32 s83, s82
	v_add_lshl_u32 v130, v0, v18, 1
	v_add_lshl_u32 v132, v1, v0, 1
	v_cvt_f32_u32_e32 v0, s83
	s_sub_i32 s39, 0, s83
	s_add_i32 s34, s38, s34
	s_abs_i32 s38, s34
	v_rcp_iflag_f32_e32 v0, v0
	s_ashr_i32 s1, s76, 6
	s_ashr_i32 s35, s34, 31
	s_ashr_i32 s86, s82, 31
	v_mul_f32_e32 v0, 0x4f7ffffe, v0
	v_cvt_u32_f32_e32 v0, v0
	s_ashr_i32 s37, s76, 8
	s_ashr_i32 s100, s76, 8
	s_lshl_b32 s6, s0, 8
	s_lshl_b32 s84, s0, 9
	v_readfirstlane_b32 s87, v0
	s_mul_i32 s39, s39, s87
	s_mul_hi_u32 s39, s87, s39
	s_add_i32 s87, s87, s39
	s_mul_hi_u32 s39, s38, s87
	s_mul_i32 s40, s39, s83
	s_sub_i32 s38, s38, s40
	s_lshl_b32 s85, s1, 10
	s_xor_b32 s35, s35, s86
	s_add_i32 s40, s39, 1
	s_sub_i32 s41, s38, s83
	s_cmp_ge_u32 s38, s83
	s_cselect_b32 s39, s40, s39
	s_cselect_b32 s38, s41, s38
	s_add_i32 s40, s39, 1
	s_cmp_ge_u32 s38, s83
	s_cselect_b32 s38, s40, s39
	s_xor_b32 s38, s38, s35
	s_sub_i32 s35, s38, s35
	s_lshl_b32 s39, s35, 3
	s_sub_i32 s38, s73, s39
	s_min_i32 s40, s38, 8
	s_sext_i32_i16 s38, s40
	v_cvt_f32_i32_e32 v0, s38
	s_mul_i32 s35, s35, s82
	s_sub_i32 s41, s34, s35
	v_cvt_f32_i32_e32 v1, s41
	v_rcp_iflag_f32_e32 v2, v0
	s_xor_b32 s34, s41, s38
	s_ashr_i32 s34, s34, 30
	s_or_b32 s38, s34, 1
	v_mul_f32_e32 v2, v1, v2
	v_trunc_f32_e32 v2, v2
	v_fma_f32 v1, -v2, v0, v1
	v_cvt_i32_f32_e32 v2, v2
	v_cmp_ge_f32_e64 s[34:35], |v1|, |v0|
	s_and_b64 s[34:35], s[34:35], exec
	s_cselect_b32 s34, s38, 0
	v_readfirstlane_b32 s35, v2
	s_add_i32 s38, s35, s34
	s_mul_i32 s34, s38, s40
	s_sub_i32 s34, s41, s34
	s_sext_i32_i16 s34, s34
	s_add_i32 s60, s39, s34
	s_mul_hi_i32 s39, s84, s60
	s_bfe_i64 s[34:35], s[38:39], 0x100000
	s_mul_hi_i32 s35, s84, s34
	s_mul_i32 s34, s84, s34
	s_add_u32 s34, s52, s34
	s_addc_u32 s35, s53, s35
	s_add_i32 s88, s85, 0
	s_add_i32 m0, s88, 0x10000
	s_mul_i32 s40, s84, s60
	global_load_lds_dwordx4 v154, s[34:35]
	s_add_i32 m0, s88, 0x12000
	s_add_u32 s44, s50, s40
	global_load_lds_dwordx4 v132, s[34:35]
	s_addc_u32 s45, s51, s39
	s_mov_b32 m0, s88
	s_add_i32 s89, s88, 0x2000
	global_load_lds_dwordx4 v128, s[44:45]
	s_mov_b32 m0, s89
	s_add_u32 s40, s34, s6
	global_load_lds_dwordx4 v130, s[44:45]
	s_addc_u32 s41, s35, 0
	s_add_i32 m0, s88, 0x14000
	v_mov_b32_e32 v133, v155
	global_load_lds_dwordx4 v154, s[40:41]
	s_add_i32 m0, s88, 0x16000
	s_add_u32 s92, s44, s6
	s_addc_u32 s93, s45, 0
	s_add_i32 s90, s88, 0x4000
	global_load_lds_dwordx4 v132, s[40:41]
	s_mov_b32 m0, s90
	s_add_i32 s91, s88, 0x6000
	global_load_lds_dwordx4 v128, s[92:93]
	s_mov_b32 m0, s91
	v_mov_b32_e32 v129, v155
	global_load_lds_dwordx4 v130, s[92:93]
	v_mov_b32_e32 v131, v155
	v_lshl_add_u64 v[10:11], s[34:35], 0, v[154:155]
	v_lshl_add_u64 v[8:9], s[34:35], 0, v[132:133]
	v_lshl_add_u64 v[6:7], s[44:45], 0, v[128:129]
	v_lshl_add_u64 v[4:5], s[44:45], 0, v[130:131]
	v_lshl_add_u64 v[2:3], s[40:41], 0, v[154:155]
	s_cmp_lg_u32 s37, 1
	v_lshl_add_u64 v[0:1], s[40:41], 0, v[132:133]
	s_cbranch_scc1 .LBB0_88
	s_barrier

; #define PG8_STAGE(bufoff, gbase, voff) do { _Pragma("unroll") for (int _i = 0; _i < 2; ++_i) \
;         __builtin_amdgcn_global_load_lds((const unsigned*)((const char*)(gbase) + (voff)[_i]), (LAS unsigned*)(lds + (bufoff) + ldsw + _i * 8192), 16, 0, 0); } while (0)
; #define PG8_LDA(dst, b, h) do { _Pragma("unroll") for (int m = 0; m < 4; ++m) _Pragma("unroll") for (int k = 0; k < 2; ++k) dst[m][k] = *(const LAS bf16x8*)(lds + PG8_SA(b, h) + aoff + m * 2048 + k * 1024); } while (0)
; #define PG8_LDB(dst, b, h) do { _Pragma("unroll") for (int n = 0; n < 2; ++n) _Pragma("unroll") for (int k = 0; k < 2; ++k) dst[n][k] = *(const LAS bf16x8*)(lds + PG8_SB(b, h) + boff + n * 2048 + k * 1024); } while (0)
; #define PG8_MMA(ai, bj, At, Bt) do { __builtin_amdgcn_s_setprio(1); _Pragma("unroll") for (int m = 0; m < 4; ++m) _Pragma("unroll") for (int n = 0; n < 2; ++n) _Pragma("unroll") for (int k = 0; k < 2; ++k) \
;         acc[ai][bj][m][n] = __builtin_amdgcn_mfma_f32_16x16x32_bf16(Bt[n][k], At[m][k], acc[ai][bj][m][n], 0, 0, 0); __builtin_amdgcn_s_setprio(0); } while (0)
; #define PG8_WAIT_L(n) asm volatile("s_waitcnt lgkmcnt(" #n ")" ::: "memory")
; #define PG8_BAR __builtin_amdgcn_s_barrier()
; #define PG8_SCHED __builtin_amdgcn_sched_barrier(0)
; template <class Epi, class Sched>
; __device__ __forceinline__ void gemm_phase(LAS unsigned char* lds, const Gemm g, const Sched& S, const Epi& E, int tid) {
;     ...
;         for (int t = 0; t < nt; t += 2) {
;             const bool last = (t == nt - 2);
;             const char* a1 = cA + (size_t)(t + 1) * kstep;
;             const char* a2 = last ? nA : cA + (size_t)(t + 2) * kstep; const char* b2 = last ? nB : cB + (size_t)(t + 2) * kstep;
;             const char* a3 = a2 + kstep; const char* b3 = b2 + kstep;
;             PG8_LDB(B0, 0, 0); PG8_SCHED; PG8_LDA(At, 0, 0); PG8_STAGE(PG8_SA(1, 1), a1 + hstep, voffA);
;             PG8_WAIT_L(8); PG8_BAR; PG8_WAIT_L(0); PG8_MMA(0, 0, At, B0); PG8_BAR; PG8_SCHED;
;             PG8_LDB(B1, 0, 1); PG8_STAGE(PG8_SB(0, 0), b2, voffB);
;             PG8_BAR; PG8_WAIT_L(0); PG8_MMA(0, 1, At, B1); PG8_BAR;
;             PG8_LDA(At, 0, 1); PG8_STAGE(PG8_SA(0, 0), a2, voffA);
;             PG8_BAR; PG8_WAIT_L(0); PG8_MMA(1, 0, At, B0); PG8_BAR; PG8_SCHED;
.LBB0_99:
	s_add_u32 vcc_lo, s44, 0x80
	s_addc_u32 vcc_hi, s45, 0
	s_add_u32 s96, s34, 0x100
	s_addc_u32 s65, s35, 0
	s_mov_b32 s34, 0
	s_add_i32 s0, s34, 2
	s_add_u32 s1, vcc_lo, 0x80
	s_addc_u32 s35, vcc_hi, 0
	s_add_i32 s17, 0, 0x10000
	v_add_u32_e32 v152, s17, v141
	ds_read_b128 v[144:147], v152
	ds_read_b128 v[148:151], v152 offset:1024
	ds_read_b128 v[160:163], v152 offset:2048
	ds_read_b128 v[164:167], v152 offset:3072
	s_cmp_eq_u32 s95, s34
	s_cselect_b32 s34, s38, s1
	s_cselect_b32 s35, s39, s35
	s_cselect_b32 s45, s41, s65
	s_cselect_b32 s44, s40, s96
	v_lshl_add_u64 v[152:153], vcc, 0, v[134:135]
	s_add_i32 m0, s88, 0xc000
	ds_read_b128 v[168:171], v143
	ds_read_b128 v[188:191], v143 offset:2048
	ds_read_b128 v[196:199], v143 offset:4096
	ds_read_b128 v[204:207], v143 offset:6144
	global_load_lds_dwordx4 v[152:153], off
	v_lshl_add_u64 v[152:153], vcc, 0, v[136:137]
	s_add_i32 m0, s88, 0xe000
	s_nop 0
	global_load_lds_dwordx4 v[152:153], off
	s_waitcnt lgkmcnt(4)
	s_setprio 1
	s_barrier
	s_waitcnt lgkmcnt(0)
	v_mfma_f32_16x16x32_bf16 v[124:127], v[144:147], v[168:171], 0
	ds_read_b128 v[184:187], v143 offset:1024
	v_mfma_f32_16x16x32_bf16 v[120:123], v[160:163], v[168:171], 0
	ds_read_b128 v[192:195], v143 offset:3072
	v_mfma_f32_16x16x32_bf16 v[116:119], v[144:147], v[188:191], 0
	ds_read_b128 v[200:203], v143 offset:5120
	v_mfma_f32_16x16x32_bf16 v[112:115], v[160:163], v[188:191], 0
	ds_read_b128 v[208:211], v143 offset:7168
	v_mfma_f32_16x16x32_bf16 v[100:103], v[144:147], v[196:199], 0
	v_mfma_f32_16x16x32_bf16 v[96:99], v[160:163], v[196:199], 0
	v_mfma_f32_16x16x32_bf16 v[84:87], v[144:147], v[204:207], 0
	v_mfma_f32_16x16x32_bf16 v[80:83], v[160:163], v[204:207], 0
	s_waitcnt lgkmcnt(0)
	v_mfma_f32_16x16x32_bf16 v[124:127], v[148:151], v[184:187], v[124:127]
	v_mfma_f32_16x16x32_bf16 v[120:123], v[164:167], v[184:187], v[120:123]
	v_mfma_f32_16x16x32_bf16 v[116:119], v[148:151], v[192:195], v[116:119]
	v_mfma_f32_16x16x32_bf16 v[112:115], v[164:167], v[192:195], v[112:115]
	v_mfma_f32_16x16x32_bf16 v[100:103], v[148:151], v[200:203], v[100:103]
	v_mfma_f32_16x16x32_bf16 v[96:99], v[164:167], v[200:203], v[96:99]
	v_mfma_f32_16x16x32_bf16 v[84:87], v[148:151], v[208:211], v[84:87]
	v_mfma_f32_16x16x32_bf16 v[80:83], v[164:167], v[208:211], v[80:83]
	s_barrier
	s_setprio 0
	s_add_i32 s1, 0, 0x14000
	v_add_u32_e32 v152, s1, v141
	s_add_i32 s17, s17, s85
	ds_read_b128 v[212:215], v152
	ds_read_b128 v[216:219], v152 offset:1024
	ds_read_b128 v[220:223], v152 offset:2048
	ds_read_b128 v[224:227], v152 offset:3072
	v_lshl_add_u64 v[152:153], s[44:45], 0, v[154:155]
	s_mov_b32 m0, s17
	v_lshl_add_u64 v[228:229], s[44:45], 0, v[132:133]
	global_load_lds_dwordx4 v[152:153], off
	s_add_i32 m0, s17, 0x2000
	s_nop 0
	global_load_lds_dwordx4 v[228:229], off
	s_setprio 1
	s_barrier
	s_waitcnt lgkmcnt(0)
	v_mfma_f32_16x16x32_bf16 v[108:111], v[212:215], v[168:171], 0
	v_mfma_f32_16x16x32_bf16 v[104:107], v[220:223], v[168:171], 0
	v_mfma_f32_16x16x32_bf16 v[92:95], v[212:215], v[188:191], 0
	v_mfma_f32_16x16x32_bf16 v[88:91], v[220:223], v[188:191], 0
	v_mfma_f32_16x16x32_bf16 v[76:79], v[212:215], v[196:199], 0
	v_mfma_f32_16x16x32_bf16 v[72:75], v[220:223], v[196:199], 0
	s_mov_b32 m0, s88
	v_mfma_f32_16x16x32_bf16 v[68:71], v[212:215], v[204:207], 0
	v_lshl_add_u64 v[230:231], s[34:35], 0, v[128:129]
	v_mfma_f32_16x16x32_bf16 v[64:67], v[220:223], v[204:207], 0
	v_mfma_f32_16x16x32_bf16 v[108:111], v[216:219], v[184:187], v[108:111]
	v_mfma_f32_16x16x32_bf16 v[104:107], v[224:227], v[184:187], v[104:107]
	v_mfma_f32_16x16x32_bf16 v[92:95], v[216:219], v[192:195], v[92:95]
	v_mfma_f32_16x16x32_bf16 v[88:91], v[224:227], v[192:195], v[88:91]
	v_mfma_f32_16x16x32_bf16 v[76:79], v[216:219], v[200:203], v[76:79]
	v_mfma_f32_16x16x32_bf16 v[72:75], v[224:227], v[200:203], v[72:75]
	v_mfma_f32_16x16x32_bf16 v[68:71], v[216:219], v[208:211], v[68:71]
	v_mfma_f32_16x16x32_bf16 v[64:67], v[224:227], v[208:211], v[64:67]
	s_barrier
	s_setprio 0
	ds_read_b128 v[168:171], v143 offset:16384
	ds_read_b128 v[184:187], v143 offset:17408
	ds_read_b128 v[188:191], v143 offset:18432
	ds_read_b128 v[192:195], v143 offset:19456
	ds_read_b128 v[196:199], v143 offset:20480
	ds_read_b128 v[200:203], v143 offset:21504
	ds_read_b128 v[204:207], v143 offset:22528
	ds_read_b128 v[208:211], v143 offset:23552
	global_load_lds_dwordx4 v[230:231], off
	v_lshl_add_u64 v[232:233], s[34:35], 0, v[130:131]
	s_mov_b32 m0, s89
	s_nop 0
	global_load_lds_dwordx4 v[232:233], off
	s_setprio 1
	s_barrier
	s_waitcnt lgkmcnt(0)
	v_mfma_f32_16x16x32_bf16 v[60:63], v[144:147], v[168:171], 0
	v_mfma_f32_16x16x32_bf16 v[56:59], v[160:163], v[168:171], 0
	v_mfma_f32_16x16x32_bf16 v[52:55], v[144:147], v[188:191], 0
	v_mfma_f32_16x16x32_bf16 v[48:51], v[160:163], v[188:191], 0
	v_mfma_f32_16x16x32_bf16 v[36:39], v[144:147], v[196:199], 0
	v_mfma_f32_16x16x32_bf16 v[32:35], v[160:163], v[196:199], 0
	v_mfma_f32_16x16x32_bf16 v[20:23], v[144:147], v[204:207], 0
	v_mfma_f32_16x16x32_bf16 v[16:19], v[160:163], v[204:207], 0
	v_mfma_f32_16x16x32_bf16 v[60:63], v[148:151], v[184:187], v[60:63]
	v_mfma_f32_16x16x32_bf16 v[56:59], v[164:167], v[184:187], v[56:59]
	v_mfma_f32_16x16x32_bf16 v[52:55], v[148:151], v[192:195], v[52:55]
	v_mfma_f32_16x16x32_bf16 v[48:51], v[164:167], v[192:195], v[48:51]
	v_mfma_f32_16x16x32_bf16 v[36:39], v[148:151], v[200:203], v[36:39]
	v_mfma_f32_16x16x32_bf16 v[32:35], v[164:167], v[200:203], v[32:35]
	v_mfma_f32_16x16x32_bf16 v[20:23], v[148:151], v[208:211], v[20:23]
	v_mfma_f32_16x16x32_bf16 v[16:19], v[164:167], v[208:211], v[16:19]
	s_barrier
; #define PG8_STAGE(bufoff, gbase, voff) do { _Pragma("unroll") for (int _i = 0; _i < 2; ++_i) \
;         __builtin_amdgcn_global_load_lds((const unsigned*)((const char*)(gbase) + (voff)[_i]), (LAS unsigned*)(lds + (bufoff) + ldsw + _i * 8192), 16, 0, 0); } while (0)
; #define PG8_LDA(dst, b, h) do { _Pragma("unroll") for (int m = 0; m < 4; ++m) _Pragma("unroll") for (int k = 0; k < 2; ++k) dst[m][k] = *(const LAS bf16x8*)(lds + PG8_SA(b, h) + aoff + m * 2048 + k * 1024); } while (0)
; #define PG8_LDB(dst, b, h) do { _Pragma("unroll") for (int n = 0; n < 2; ++n) _Pragma("unroll") for (int k = 0; k < 2; ++k) dst[n][k] = *(const LAS bf16x8*)(lds + PG8_SB(b, h) + boff + n * 2048 + k * 1024); } while (0)
; #define PG8_MMA(ai, bj, At, Bt) do { __builtin_amdgcn_s_setprio(1); _Pragma("unroll") for (int m = 0; m < 4; ++m) _Pragma("unroll") for (int n = 0; n < 2; ++n) _Pragma("unroll") for (int k = 0; k < 2; ++k) \
;         acc[ai][bj][m][n] = __builtin_amdgcn_mfma_f32_16x16x32_bf16(Bt[n][k], At[m][k], acc[ai][bj][m][n], 0, 0, 0); __builtin_amdgcn_s_setprio(0); } while (0)
; #define PG8_WAIT_V(n) asm volatile("s_waitcnt vmcnt(" #n ")" ::: "memory")
; #define PG8_WAIT_L(n) asm volatile("s_waitcnt lgkmcnt(" #n ")" ::: "memory")
; #define PG8_BAR __builtin_amdgcn_s_barrier()
; #define PG8_SCHED __builtin_amdgcn_sched_barrier(0)
; template <class Epi, class Sched>
; __device__ __forceinline__ void gemm_phase(LAS unsigned char* lds, const Gemm g, const Sched& S, const Epi& E, int tid) {
;     ...
;             PG8_STAGE(PG8_SB(0, 1), b2 + hstep, voffB);
;             PG8_WAIT_V(6); PG8_BAR; PG8_MMA(1, 1, At, B1); PG8_BAR;
;             PG8_LDB(B0, 1, 0); PG8_SCHED; PG8_LDA(At, 1, 0); PG8_STAGE(PG8_SA(0, 1), a2 + hstep, voffA);
;             PG8_WAIT_L(8); PG8_BAR; PG8_WAIT_L(0); PG8_MMA(0, 0, At, B0); PG8_BAR; PG8_SCHED;
;             PG8_LDB(B1, 1, 1); PG8_STAGE(PG8_SB(1, 0), b3, voffB);
;             PG8_BAR; PG8_WAIT_L(0); PG8_MMA(0, 1, At, B1); PG8_BAR;
;             PG8_LDA(At, 1, 1); PG8_STAGE(PG8_SA(1, 0), a3, voffA);
;             PG8_BAR; PG8_WAIT_L(0); PG8_MMA(1, 0, At, B0); PG8_BAR; PG8_SCHED;
	s_setprio 0
	s_add_u32 s44, s44, s6
	s_addc_u32 s45, s45, 0
	s_add_i32 s1, s1, s85
	v_lshl_add_u64 v[234:235], s[44:45], 0, v[154:155]
	s_mov_b32 m0, s1
	v_lshl_add_u64 v[236:237], s[44:45], 0, v[132:133]
	global_load_lds_dwordx4 v[234:235], off
	s_add_i32 m0, s1, 0x2000
	s_nop 0
	global_load_lds_dwordx4 v[236:237], off
	s_waitcnt vmcnt(24)
	s_setprio 1
	s_barrier
	v_mfma_f32_16x16x32_bf16 v[44:47], v[212:215], v[168:171], 0
	v_mfma_f32_16x16x32_bf16 v[40:43], v[220:223], v[168:171], 0
	v_mfma_f32_16x16x32_bf16 v[28:31], v[212:215], v[188:191], 0
	v_mfma_f32_16x16x32_bf16 v[24:27], v[220:223], v[188:191], 0
	v_mfma_f32_16x16x32_bf16 v[12:15], v[212:215], v[196:199], 0
	v_mfma_f32_16x16x32_bf16 v[8:11], v[220:223], v[196:199], 0
	s_add_i32 s1, 0, 0x18000
	v_mfma_f32_16x16x32_bf16 v[4:7], v[212:215], v[204:207], 0
	v_add_u32_e32 v164, s1, v141
	v_mfma_f32_16x16x32_bf16 v[0:3], v[220:223], v[204:207], 0
	v_mfma_f32_16x16x32_bf16 v[44:47], v[216:219], v[184:187], v[44:47]
	v_mfma_f32_16x16x32_bf16 v[40:43], v[224:227], v[184:187], v[40:43]
	v_mfma_f32_16x16x32_bf16 v[28:31], v[216:219], v[192:195], v[28:31]
	v_mfma_f32_16x16x32_bf16 v[24:27], v[224:227], v[192:195], v[24:27]
	v_mfma_f32_16x16x32_bf16 v[12:15], v[216:219], v[200:203], v[12:15]
	v_mfma_f32_16x16x32_bf16 v[8:11], v[224:227], v[200:203], v[8:11]
	v_mfma_f32_16x16x32_bf16 v[4:7], v[216:219], v[208:211], v[4:7]
	v_mfma_f32_16x16x32_bf16 v[0:3], v[224:227], v[208:211], v[0:3]
	s_barrier
	s_setprio 0
	ds_read_b128 v[144:147], v164
	ds_read_b128 v[148:151], v164 offset:1024
	ds_read_b128 v[160:163], v164 offset:2048
	ds_read_b128 v[164:167], v164 offset:3072
	s_add_u32 s34, s34, s6
	s_addc_u32 s35, s35, 0
	s_mov_b32 m0, s90
	v_lshl_add_u64 v[212:213], s[34:35], 0, v[128:129]
	ds_read_b128 v[168:171], v143 offset:32768
	ds_read_b128 v[188:191], v143 offset:34816
	ds_read_b128 v[196:199], v143 offset:36864
	ds_read_b128 v[204:207], v143 offset:38912
	global_load_lds_dwordx4 v[212:213], off
	v_lshl_add_u64 v[212:213], s[34:35], 0, v[130:131]
	s_mov_b32 m0, s91
	s_nop 0
	global_load_lds_dwordx4 v[212:213], off
	s_waitcnt lgkmcnt(4)
	s_setprio 1
	s_barrier
	s_waitcnt lgkmcnt(0)
	v_mfma_f32_16x16x32_bf16 v[124:127], v[144:147], v[168:171], v[124:127]
	ds_read_b128 v[184:187], v143 offset:33792
	v_mfma_f32_16x16x32_bf16 v[120:123], v[160:163], v[168:171], v[120:123]
	ds_read_b128 v[192:195], v143 offset:35840
	v_mfma_f32_16x16x32_bf16 v[116:119], v[144:147], v[188:191], v[116:119]
	ds_read_b128 v[200:203], v143 offset:37888
	v_mfma_f32_16x16x32_bf16 v[112:115], v[160:163], v[188:191], v[112:115]
	ds_read_b128 v[208:211], v143 offset:39936
	v_mfma_f32_16x16x32_bf16 v[100:103], v[144:147], v[196:199], v[100:103]
	v_mfma_f32_16x16x32_bf16 v[96:99], v[160:163], v[196:199], v[96:99]
	v_mfma_f32_16x16x32_bf16 v[84:87], v[144:147], v[204:207], v[84:87]
	v_mfma_f32_16x16x32_bf16 v[80:83], v[160:163], v[204:207], v[80:83]
	s_waitcnt lgkmcnt(0)
	v_mfma_f32_16x16x32_bf16 v[124:127], v[148:151], v[184:187], v[124:127]
	v_mfma_f32_16x16x32_bf16 v[120:123], v[164:167], v[184:187], v[120:123]
	v_mfma_f32_16x16x32_bf16 v[116:119], v[148:151], v[192:195], v[116:119]
	v_mfma_f32_16x16x32_bf16 v[112:115], v[164:167], v[192:195], v[112:115]
	v_mfma_f32_16x16x32_bf16 v[100:103], v[148:151], v[200:203], v[100:103]
	v_mfma_f32_16x16x32_bf16 v[96:99], v[164:167], v[200:203], v[96:99]
	v_mfma_f32_16x16x32_bf16 v[84:87], v[148:151], v[208:211], v[84:87]
	v_mfma_f32_16x16x32_bf16 v[80:83], v[164:167], v[208:211], v[80:83]
	s_barrier
	s_setprio 0
	s_add_i32 s17, 0, 0x1c000
	s_add_i32 s1, s1, s85
	v_add_u32_e32 v183, s17, v141
	v_lshl_add_u64 v[152:153], v[152:153], 0, s[8:9]
	s_mov_b32 m0, s1
	ds_read_b128 v[212:215], v183
	ds_read_b128 v[216:219], v183 offset:1024
	ds_read_b128 v[220:223], v183 offset:2048
	ds_read_b128 v[224:227], v183 offset:3072
	global_load_lds_dwordx4 v[152:153], off
	v_lshl_add_u64 v[152:153], v[228:229], 0, s[8:9]
	s_add_i32 m0, s1, 0x2000
	s_nop 0
	global_load_lds_dwordx4 v[152:153], off
	s_waitcnt vmcnt(10)
	s_setprio 1
	s_barrier
	s_waitcnt lgkmcnt(0)
	v_mfma_f32_16x16x32_bf16 v[108:111], v[212:215], v[168:171], v[108:111]
	v_mfma_f32_16x16x32_bf16 v[104:107], v[220:223], v[168:171], v[104:107]
	v_mfma_f32_16x16x32_bf16 v[92:95], v[212:215], v[188:191], v[92:95]
	v_mfma_f32_16x16x32_bf16 v[88:91], v[220:223], v[188:191], v[88:91]
	v_mfma_f32_16x16x32_bf16 v[76:79], v[212:215], v[196:199], v[76:79]
	v_mfma_f32_16x16x32_bf16 v[72:75], v[220:223], v[196:199], v[72:75]
	s_mov_b32 m0, s92
	v_mfma_f32_16x16x32_bf16 v[68:71], v[212:215], v[204:207], v[68:71]
	v_lshl_add_u64 v[152:153], v[230:231], 0, s[8:9]
	v_mfma_f32_16x16x32_bf16 v[64:67], v[220:223], v[204:207], v[64:67]
	v_mfma_f32_16x16x32_bf16 v[108:111], v[216:219], v[184:187], v[108:111]
	v_mfma_f32_16x16x32_bf16 v[104:107], v[224:227], v[184:187], v[104:107]
	v_mfma_f32_16x16x32_bf16 v[92:95], v[216:219], v[192:195], v[92:95]
	v_mfma_f32_16x16x32_bf16 v[88:91], v[224:227], v[192:195], v[88:91]
	v_mfma_f32_16x16x32_bf16 v[76:79], v[216:219], v[200:203], v[76:79]
	v_mfma_f32_16x16x32_bf16 v[72:75], v[224:227], v[200:203], v[72:75]
	v_mfma_f32_16x16x32_bf16 v[68:71], v[216:219], v[208:211], v[68:71]
	v_mfma_f32_16x16x32_bf16 v[64:67], v[224:227], v[208:211], v[64:67]
	s_barrier
	s_setprio 0
	ds_read_b128 v[168:171], v143 offset:49152
	ds_read_b128 v[184:187], v143 offset:50176
	ds_read_b128 v[188:191], v143 offset:51200
	ds_read_b128 v[192:195], v143 offset:52224
	ds_read_b128 v[196:199], v143 offset:53248
	ds_read_b128 v[200:203], v143 offset:54272
	ds_read_b128 v[204:207], v143 offset:55296
	ds_read_b128 v[208:211], v143 offset:56320
	global_load_lds_dwordx4 v[152:153], off
	v_lshl_add_u64 v[152:153], v[232:233], 0, s[8:9]
	s_mov_b32 m0, s93
	s_nop 0
	global_load_lds_dwordx4 v[152:153], off
	s_setprio 1
	s_barrier
; #define PG8_STAGE(bufoff, gbase, voff) do { _Pragma("unroll") for (int _i = 0; _i < 2; ++_i) \
;         __builtin_amdgcn_global_load_lds((const unsigned*)((const char*)(gbase) + (voff)[_i]), (LAS unsigned*)(lds + (bufoff) + ldsw + _i * 8192), 16, 0, 0); } while (0)
; #define PG8_LDA(dst, b, h) do { _Pragma("unroll") for (int m = 0; m < 4; ++m) _Pragma("unroll") for (int k = 0; k < 2; ++k) dst[m][k] = *(const LAS bf16x8*)(lds + PG8_SA(b, h) + aoff + m * 2048 + k * 1024); } while (0)
; #define PG8_LDB(dst, b, h) do { _Pragma("unroll") for (int n = 0; n < 2; ++n) _Pragma("unroll") for (int k = 0; k < 2; ++k) dst[n][k] = *(const LAS bf16x8*)(lds + PG8_SB(b, h) + boff + n * 2048 + k * 1024); } while (0)
; #define PG8_MMA(ai, bj, At, Bt) do { __builtin_amdgcn_s_setprio(1); _Pragma("unroll") for (int m = 0; m < 4; ++m) _Pragma("unroll") for (int n = 0; n < 2; ++n) _Pragma("unroll") for (int k = 0; k < 2; ++k) \
;         acc[ai][bj][m][n] = __builtin_amdgcn_mfma_f32_16x16x32_bf16(Bt[n][k], At[m][k], acc[ai][bj][m][n], 0, 0, 0); __builtin_amdgcn_s_setprio(0); } while (0)
; #define PG8_WAIT_V(n) asm volatile("s_waitcnt vmcnt(" #n ")" ::: "memory")
; #define PG8_WAIT_L(n) asm volatile("s_waitcnt lgkmcnt(" #n ")" ::: "memory")
; #define PG8_BAR __builtin_amdgcn_s_barrier()
; #define PG8_SCHED __builtin_amdgcn_sched_barrier(0)
; template <class Epi, class Sched>
; __device__ __forceinline__ void gemm_phase(LAS unsigned char* lds, const Gemm g, const Sched& S, const Epi& E, int tid) {
;     ...
;             PG8_LDB(B0, 0, 0); PG8_SCHED; PG8_LDA(At, 0, 0); PG8_STAGE(PG8_SA(1, 1), a1 + hstep, voffA);
;             PG8_WAIT_L(8); PG8_BAR; PG8_WAIT_L(0); PG8_MMA(0, 0, At, B0); PG8_BAR; PG8_SCHED;
;             PG8_LDB(B1, 0, 1); PG8_STAGE(PG8_SB(0, 0), b2, voffB);
;     ...
;             PG8_BAR; PG8_WAIT_L(0); PG8_MMA(1, 0, At, B0); PG8_BAR; PG8_SCHED;
;             PG8_STAGE(PG8_SB(1, 1), b3 + hstep, voffB);
;             PG8_WAIT_V(6); PG8_BAR; PG8_MMA(1, 1, At, B1); PG8_BAR;
;         }
;         E(acc, cur, wr, wc, fr, fq);
;         if (!has_next) break;
	s_waitcnt lgkmcnt(0)
	v_mfma_f32_16x16x32_bf16 v[60:63], v[144:147], v[168:171], v[60:63]
	v_mfma_f32_16x16x32_bf16 v[56:59], v[160:163], v[168:171], v[56:59]
	v_mfma_f32_16x16x32_bf16 v[52:55], v[144:147], v[188:191], v[52:55]
	v_mfma_f32_16x16x32_bf16 v[48:51], v[160:163], v[188:191], v[48:51]
	v_mfma_f32_16x16x32_bf16 v[36:39], v[144:147], v[196:199], v[36:39]
	v_mfma_f32_16x16x32_bf16 v[32:35], v[160:163], v[196:199], v[32:35]
	v_mfma_f32_16x16x32_bf16 v[20:23], v[144:147], v[204:207], v[20:23]
	v_mfma_f32_16x16x32_bf16 v[16:19], v[160:163], v[204:207], v[16:19]
	v_mfma_f32_16x16x32_bf16 v[60:63], v[148:151], v[184:187], v[60:63]
	v_mfma_f32_16x16x32_bf16 v[56:59], v[164:167], v[184:187], v[56:59]
	v_mfma_f32_16x16x32_bf16 v[52:55], v[148:151], v[192:195], v[52:55]
	v_mfma_f32_16x16x32_bf16 v[48:51], v[164:167], v[192:195], v[48:51]
	v_mfma_f32_16x16x32_bf16 v[36:39], v[148:151], v[200:203], v[36:39]
	v_mfma_f32_16x16x32_bf16 v[32:35], v[164:167], v[200:203], v[32:35]
	v_mfma_f32_16x16x32_bf16 v[20:23], v[148:151], v[208:211], v[20:23]
	v_mfma_f32_16x16x32_bf16 v[16:19], v[164:167], v[208:211], v[16:19]
	s_barrier
	s_setprio 0
	s_add_i32 s1, s17, s85
	v_lshl_add_u64 v[144:145], v[234:235], 0, s[8:9]
	s_mov_b32 m0, s1
	s_nop 0
	global_load_lds_dwordx4 v[144:145], off
	v_lshl_add_u64 v[144:145], v[236:237], 0, s[8:9]
	s_add_i32 m0, s1, 0x2000
	s_nop 0
	global_load_lds_dwordx4 v[144:145], off
	s_waitcnt vmcnt(6)
	s_setprio 1
	s_barrier
	v_mfma_f32_16x16x32_bf16 v[44:47], v[212:215], v[168:171], v[44:47]
	v_mfma_f32_16x16x32_bf16 v[40:43], v[220:223], v[168:171], v[40:43]
	v_mfma_f32_16x16x32_bf16 v[28:31], v[212:215], v[188:191], v[28:31]
	v_mfma_f32_16x16x32_bf16 v[24:27], v[220:223], v[188:191], v[24:27]
	v_mfma_f32_16x16x32_bf16 v[12:15], v[212:215], v[196:199], v[12:15]
	v_mfma_f32_16x16x32_bf16 v[8:11], v[220:223], v[196:199], v[8:11]
	s_add_u32 vcc_lo, vcc_lo, 0x100
	v_mfma_f32_16x16x32_bf16 v[4:7], v[212:215], v[204:207], v[4:7]
	s_addc_u32 vcc_hi, vcc_hi, 0
	v_mfma_f32_16x16x32_bf16 v[0:3], v[220:223], v[204:207], v[0:3]
	s_add_u32 s96, s96, 0x100
	v_mfma_f32_16x16x32_bf16 v[44:47], v[216:219], v[184:187], v[44:47]
	s_addc_u32 s65, s65, 0
	v_mfma_f32_16x16x32_bf16 v[40:43], v[224:227], v[184:187], v[40:43]
	s_cmp_ge_u32 s0, s94
	v_mfma_f32_16x16x32_bf16 v[28:31], v[216:219], v[192:195], v[28:31]
	s_mov_b32 s34, s0
	v_mfma_f32_16x16x32_bf16 v[24:27], v[224:227], v[192:195], v[24:27]
	v_mfma_f32_16x16x32_bf16 v[12:15], v[216:219], v[200:203], v[12:15]
	v_mfma_f32_16x16x32_bf16 v[8:11], v[224:227], v[200:203], v[8:11]
	v_mfma_f32_16x16x32_bf16 v[4:7], v[216:219], v[208:211], v[4:7]
	v_mfma_f32_16x16x32_bf16 v[0:3], v[224:227], v[208:211], v[0:3]
	s_cbranch_scc1 .Lx_nobar_plain
	s_barrier
	s_setprio 0
.LBB0_100:
	s_add_i32 s0, s34, 2
	s_add_u32 s1, vcc_lo, 0x80
	s_addc_u32 s35, vcc_hi, 0
	s_add_i32 s17, 0, 0x10000
	v_add_u32_e32 v152, s17, v141
	ds_read_b128 v[144:147], v152
	ds_read_b128 v[148:151], v152 offset:1024
	ds_read_b128 v[160:163], v152 offset:2048
	ds_read_b128 v[164:167], v152 offset:3072
	s_cmp_eq_u32 s95, s34
	s_cselect_b32 s34, s38, s1
	s_cselect_b32 s35, s39, s35
	s_cselect_b32 s45, s41, s65
	s_cselect_b32 s44, s40, s96
	v_lshl_add_u64 v[152:153], vcc, 0, v[134:135]
	s_add_i32 m0, s88, 0xc000
	ds_read_b128 v[168:171], v143
	ds_read_b128 v[188:191], v143 offset:2048
	ds_read_b128 v[196:199], v143 offset:4096
	ds_read_b128 v[204:207], v143 offset:6144
	global_load_lds_dwordx4 v[152:153], off
	v_lshl_add_u64 v[152:153], vcc, 0, v[136:137]
	s_add_i32 m0, s88, 0xe000
	s_nop 0
	global_load_lds_dwordx4 v[152:153], off
	s_waitcnt lgkmcnt(4)
	s_setprio 1
	s_barrier
	s_waitcnt lgkmcnt(0)
	v_mfma_f32_16x16x32_bf16 v[124:127], v[144:147], v[168:171], v[124:127]
	ds_read_b128 v[184:187], v143 offset:1024
	v_mfma_f32_16x16x32_bf16 v[120:123], v[160:163], v[168:171], v[120:123]
	ds_read_b128 v[192:195], v143 offset:3072
	v_mfma_f32_16x16x32_bf16 v[116:119], v[144:147], v[188:191], v[116:119]
	ds_read_b128 v[200:203], v143 offset:5120
	v_mfma_f32_16x16x32_bf16 v[112:115], v[160:163], v[188:191], v[112:115]
	ds_read_b128 v[208:211], v143 offset:7168
	v_mfma_f32_16x16x32_bf16 v[100:103], v[144:147], v[196:199], v[100:103]
	v_mfma_f32_16x16x32_bf16 v[96:99], v[160:163], v[196:199], v[96:99]
	v_mfma_f32_16x16x32_bf16 v[84:87], v[144:147], v[204:207], v[84:87]
	v_mfma_f32_16x16x32_bf16 v[80:83], v[160:163], v[204:207], v[80:83]
	s_waitcnt lgkmcnt(0)
	v_mfma_f32_16x16x32_bf16 v[124:127], v[148:151], v[184:187], v[124:127]
	v_mfma_f32_16x16x32_bf16 v[120:123], v[164:167], v[184:187], v[120:123]
	v_mfma_f32_16x16x32_bf16 v[116:119], v[148:151], v[192:195], v[116:119]
	v_mfma_f32_16x16x32_bf16 v[112:115], v[164:167], v[192:195], v[112:115]
	v_mfma_f32_16x16x32_bf16 v[100:103], v[148:151], v[200:203], v[100:103]
	v_mfma_f32_16x16x32_bf16 v[96:99], v[164:167], v[200:203], v[96:99]
	v_mfma_f32_16x16x32_bf16 v[84:87], v[148:151], v[208:211], v[84:87]
	v_mfma_f32_16x16x32_bf16 v[80:83], v[164:167], v[208:211], v[80:83]
	s_barrier
	s_setprio 0
	s_add_i32 s1, 0, 0x14000
	v_add_u32_e32 v152, s1, v141
	s_add_i32 s17, s17, s85
	ds_read_b128 v[212:215], v152
	ds_read_b128 v[216:219], v152 offset:1024
	ds_read_b128 v[220:223], v152 offset:2048
	ds_read_b128 v[224:227], v152 offset:3072
	v_lshl_add_u64 v[152:153], s[44:45], 0, v[154:155]
	s_mov_b32 m0, s17
	v_lshl_add_u64 v[228:229], s[44:45], 0, v[132:133]
	global_load_lds_dwordx4 v[152:153], off
	s_add_i32 m0, s17, 0x2000
	s_nop 0
	global_load_lds_dwordx4 v[228:229], off
	s_setprio 1
	s_barrier
; #define PG8_STAGE(bufoff, gbase, voff) do { _Pragma("unroll") for (int _i = 0; _i < 2; ++_i) \
;         __builtin_amdgcn_global_load_lds((const unsigned*)((const char*)(gbase) + (voff)[_i]), (LAS unsigned*)(lds + (bufoff) + ldsw + _i * 8192), 16, 0, 0); } while (0)
; #define PG8_LDA(dst, b, h) do { _Pragma("unroll") for (int m = 0; m < 4; ++m) _Pragma("unroll") for (int k = 0; k < 2; ++k) dst[m][k] = *(const LAS bf16x8*)(lds + PG8_SA(b, h) + aoff + m * 2048 + k * 1024); } while (0)
; #define PG8_LDB(dst, b, h) do { _Pragma("unroll") for (int n = 0; n < 2; ++n) _Pragma("unroll") for (int k = 0; k < 2; ++k) dst[n][k] = *(const LAS bf16x8*)(lds + PG8_SB(b, h) + boff + n * 2048 + k * 1024); } while (0)
; #define PG8_MMA(ai, bj, At, Bt) do { __builtin_amdgcn_s_setprio(1); _Pragma("unroll") for (int m = 0; m < 4; ++m) _Pragma("unroll") for (int n = 0; n < 2; ++n) _Pragma("unroll") for (int k = 0; k < 2; ++k) \
;         acc[ai][bj][m][n] = __builtin_amdgcn_mfma_f32_16x16x32_bf16(Bt[n][k], At[m][k], acc[ai][bj][m][n], 0, 0, 0); __builtin_amdgcn_s_setprio(0); } while (0)
; #define PG8_WAIT_V(n) asm volatile("s_waitcnt vmcnt(" #n ")" ::: "memory")
; #define PG8_WAIT_L(n) asm volatile("s_waitcnt lgkmcnt(" #n ")" ::: "memory")
; #define PG8_BAR __builtin_amdgcn_s_barrier()
; #define PG8_SCHED __builtin_amdgcn_sched_barrier(0)
; template <class Epi, class Sched>
; __device__ __forceinline__ void gemm_phase(LAS unsigned char* lds, const Gemm g, const Sched& S, const Epi& E, int tid) {
;     ...
;             PG8_BAR; PG8_WAIT_L(0); PG8_MMA(0, 1, At, B1); PG8_BAR;
;             PG8_LDA(At, 0, 1); PG8_STAGE(PG8_SA(0, 0), a2, voffA);
;             PG8_BAR; PG8_WAIT_L(0); PG8_MMA(1, 0, At, B0); PG8_BAR; PG8_SCHED;
;             PG8_STAGE(PG8_SB(0, 1), b2 + hstep, voffB);
;             PG8_WAIT_V(6); PG8_BAR; PG8_MMA(1, 1, At, B1); PG8_BAR;
;             PG8_LDB(B0, 1, 0); PG8_SCHED; PG8_LDA(At, 1, 0); PG8_STAGE(PG8_SA(0, 1), a2 + hstep, voffA);
;             PG8_WAIT_L(8); PG8_BAR; PG8_WAIT_L(0); PG8_MMA(0, 0, At, B0); PG8_BAR; PG8_SCHED;
	s_waitcnt lgkmcnt(0)
	v_mfma_f32_16x16x32_bf16 v[108:111], v[212:215], v[168:171], v[108:111]
	v_mfma_f32_16x16x32_bf16 v[104:107], v[220:223], v[168:171], v[104:107]
	v_mfma_f32_16x16x32_bf16 v[92:95], v[212:215], v[188:191], v[92:95]
	v_mfma_f32_16x16x32_bf16 v[88:91], v[220:223], v[188:191], v[88:91]
	v_mfma_f32_16x16x32_bf16 v[76:79], v[212:215], v[196:199], v[76:79]
	v_mfma_f32_16x16x32_bf16 v[72:75], v[220:223], v[196:199], v[72:75]
	s_mov_b32 m0, s88
	v_mfma_f32_16x16x32_bf16 v[68:71], v[212:215], v[204:207], v[68:71]
	v_lshl_add_u64 v[230:231], s[34:35], 0, v[128:129]
	v_mfma_f32_16x16x32_bf16 v[64:67], v[220:223], v[204:207], v[64:67]
	v_mfma_f32_16x16x32_bf16 v[108:111], v[216:219], v[184:187], v[108:111]
	v_mfma_f32_16x16x32_bf16 v[104:107], v[224:227], v[184:187], v[104:107]
	v_mfma_f32_16x16x32_bf16 v[92:95], v[216:219], v[192:195], v[92:95]
	v_mfma_f32_16x16x32_bf16 v[88:91], v[224:227], v[192:195], v[88:91]
	v_mfma_f32_16x16x32_bf16 v[76:79], v[216:219], v[200:203], v[76:79]
	v_mfma_f32_16x16x32_bf16 v[72:75], v[224:227], v[200:203], v[72:75]
	v_mfma_f32_16x16x32_bf16 v[68:71], v[216:219], v[208:211], v[68:71]
	v_mfma_f32_16x16x32_bf16 v[64:67], v[224:227], v[208:211], v[64:67]
	s_barrier
	s_setprio 0
	ds_read_b128 v[168:171], v143 offset:16384
	ds_read_b128 v[184:187], v143 offset:17408
	ds_read_b128 v[188:191], v143 offset:18432
	ds_read_b128 v[192:195], v143 offset:19456
	ds_read_b128 v[196:199], v143 offset:20480
	ds_read_b128 v[200:203], v143 offset:21504
	ds_read_b128 v[204:207], v143 offset:22528
	ds_read_b128 v[208:211], v143 offset:23552
	global_load_lds_dwordx4 v[230:231], off
	v_lshl_add_u64 v[232:233], s[34:35], 0, v[130:131]
	s_mov_b32 m0, s89
	s_nop 0
	global_load_lds_dwordx4 v[232:233], off
	s_setprio 1
	s_barrier
	s_waitcnt lgkmcnt(0)
	v_mfma_f32_16x16x32_bf16 v[60:63], v[144:147], v[168:171], v[60:63]
	v_mfma_f32_16x16x32_bf16 v[56:59], v[160:163], v[168:171], v[56:59]
	v_mfma_f32_16x16x32_bf16 v[52:55], v[144:147], v[188:191], v[52:55]
	v_mfma_f32_16x16x32_bf16 v[48:51], v[160:163], v[188:191], v[48:51]
	v_mfma_f32_16x16x32_bf16 v[36:39], v[144:147], v[196:199], v[36:39]
	v_mfma_f32_16x16x32_bf16 v[32:35], v[160:163], v[196:199], v[32:35]
	v_mfma_f32_16x16x32_bf16 v[20:23], v[144:147], v[204:207], v[20:23]
	v_mfma_f32_16x16x32_bf16 v[16:19], v[160:163], v[204:207], v[16:19]
	v_mfma_f32_16x16x32_bf16 v[60:63], v[148:151], v[184:187], v[60:63]
	v_mfma_f32_16x16x32_bf16 v[56:59], v[164:167], v[184:187], v[56:59]
	v_mfma_f32_16x16x32_bf16 v[52:55], v[148:151], v[192:195], v[52:55]
	v_mfma_f32_16x16x32_bf16 v[48:51], v[164:167], v[192:195], v[48:51]
	v_mfma_f32_16x16x32_bf16 v[36:39], v[148:151], v[200:203], v[36:39]
	v_mfma_f32_16x16x32_bf16 v[32:35], v[164:167], v[200:203], v[32:35]
	v_mfma_f32_16x16x32_bf16 v[20:23], v[148:151], v[208:211], v[20:23]
	v_mfma_f32_16x16x32_bf16 v[16:19], v[164:167], v[208:211], v[16:19]
	s_barrier
	s_setprio 0
	s_add_u32 s44, s44, s6
	s_addc_u32 s45, s45, 0
	s_add_i32 s1, s1, s85
	v_lshl_add_u64 v[234:235], s[44:45], 0, v[154:155]
	s_mov_b32 m0, s1
	v_lshl_add_u64 v[236:237], s[44:45], 0, v[132:133]
	global_load_lds_dwordx4 v[234:235], off
	s_add_i32 m0, s1, 0x2000
	s_nop 0
	global_load_lds_dwordx4 v[236:237], off
	s_waitcnt vmcnt(6)
	s_setprio 1
	s_barrier
	v_mfma_f32_16x16x32_bf16 v[44:47], v[212:215], v[168:171], v[44:47]
	v_mfma_f32_16x16x32_bf16 v[40:43], v[220:223], v[168:171], v[40:43]
	v_mfma_f32_16x16x32_bf16 v[28:31], v[212:215], v[188:191], v[28:31]
	v_mfma_f32_16x16x32_bf16 v[24:27], v[220:223], v[188:191], v[24:27]
	v_mfma_f32_16x16x32_bf16 v[12:15], v[212:215], v[196:199], v[12:15]
	v_mfma_f32_16x16x32_bf16 v[8:11], v[220:223], v[196:199], v[8:11]
	s_add_i32 s1, 0, 0x18000
	v_mfma_f32_16x16x32_bf16 v[4:7], v[212:215], v[204:207], v[4:7]
	v_add_u32_e32 v164, s1, v141
	v_mfma_f32_16x16x32_bf16 v[0:3], v[220:223], v[204:207], v[0:3]
	v_mfma_f32_16x16x32_bf16 v[44:47], v[216:219], v[184:187], v[44:47]
	v_mfma_f32_16x16x32_bf16 v[40:43], v[224:227], v[184:187], v[40:43]
	v_mfma_f32_16x16x32_bf16 v[28:31], v[216:219], v[192:195], v[28:31]
	v_mfma_f32_16x16x32_bf16 v[24:27], v[224:227], v[192:195], v[24:27]
	v_mfma_f32_16x16x32_bf16 v[12:15], v[216:219], v[200:203], v[12:15]
	v_mfma_f32_16x16x32_bf16 v[8:11], v[224:227], v[200:203], v[8:11]
	v_mfma_f32_16x16x32_bf16 v[4:7], v[216:219], v[208:211], v[4:7]
	v_mfma_f32_16x16x32_bf16 v[0:3], v[224:227], v[208:211], v[0:3]
	s_barrier
	s_setprio 0
	ds_read_b128 v[144:147], v164
	ds_read_b128 v[148:151], v164 offset:1024
	ds_read_b128 v[160:163], v164 offset:2048
	ds_read_b128 v[164:167], v164 offset:3072
	s_add_u32 s34, s34, s6
	s_addc_u32 s35, s35, 0
	s_mov_b32 m0, s90
	v_lshl_add_u64 v[212:213], s[34:35], 0, v[128:129]
	ds_read_b128 v[168:171], v143 offset:32768
	ds_read_b128 v[188:191], v143 offset:34816
	ds_read_b128 v[196:199], v143 offset:36864
	ds_read_b128 v[204:207], v143 offset:38912
	global_load_lds_dwordx4 v[212:213], off
	v_lshl_add_u64 v[212:213], s[34:35], 0, v[130:131]
	s_mov_b32 m0, s91
	s_nop 0
	global_load_lds_dwordx4 v[212:213], off
	s_waitcnt lgkmcnt(4)
	s_setprio 1
	s_barrier
; #define PG8_STAGE(bufoff, gbase, voff) do { _Pragma("unroll") for (int _i = 0; _i < 2; ++_i) \
;         __builtin_amdgcn_global_load_lds((const unsigned*)((const char*)(gbase) + (voff)[_i]), (LAS unsigned*)(lds + (bufoff) + ldsw + _i * 8192), 16, 0, 0); } while (0)
; #define PG8_LDA(dst, b, h) do { _Pragma("unroll") for (int m = 0; m < 4; ++m) _Pragma("unroll") for (int k = 0; k < 2; ++k) dst[m][k] = *(const LAS bf16x8*)(lds + PG8_SA(b, h) + aoff + m * 2048 + k * 1024); } while (0)
; #define PG8_LDB(dst, b, h) do { _Pragma("unroll") for (int n = 0; n < 2; ++n) _Pragma("unroll") for (int k = 0; k < 2; ++k) dst[n][k] = *(const LAS bf16x8*)(lds + PG8_SB(b, h) + boff + n * 2048 + k * 1024); } while (0)
; #define PG8_MMA(ai, bj, At, Bt) do { __builtin_amdgcn_s_setprio(1); _Pragma("unroll") for (int m = 0; m < 4; ++m) _Pragma("unroll") for (int n = 0; n < 2; ++n) _Pragma("unroll") for (int k = 0; k < 2; ++k) \
;         acc[ai][bj][m][n] = __builtin_amdgcn_mfma_f32_16x16x32_bf16(Bt[n][k], At[m][k], acc[ai][bj][m][n], 0, 0, 0); __builtin_amdgcn_s_setprio(0); } while (0)
; #define PG8_WAIT_V(n) asm volatile("s_waitcnt vmcnt(" #n ")" ::: "memory")
; #define PG8_WAIT_L(n) asm volatile("s_waitcnt lgkmcnt(" #n ")" ::: "memory")
; #define PG8_BAR __builtin_amdgcn_s_barrier()
; #define PG8_SCHED __builtin_amdgcn_sched_barrier(0)
; template <class Epi, class Sched>
; __device__ __forceinline__ void gemm_phase(LAS unsigned char* lds, const Gemm g, const Sched& S, const Epi& E, int tid) {
;     ...
;             PG8_WAIT_L(8); PG8_BAR; PG8_WAIT_L(0); PG8_MMA(0, 0, At, B0); PG8_BAR; PG8_SCHED;
;             PG8_LDB(B1, 1, 1); PG8_STAGE(PG8_SB(1, 0), b3, voffB);
;             PG8_BAR; PG8_WAIT_L(0); PG8_MMA(0, 1, At, B1); PG8_BAR;
;             PG8_LDA(At, 1, 1); PG8_STAGE(PG8_SA(1, 0), a3, voffA);
;             PG8_BAR; PG8_WAIT_L(0); PG8_MMA(1, 0, At, B0); PG8_BAR; PG8_SCHED;
;             PG8_STAGE(PG8_SB(1, 1), b3 + hstep, voffB);
;             PG8_WAIT_V(6); PG8_BAR; PG8_MMA(1, 1, At, B1); PG8_BAR;
	s_waitcnt lgkmcnt(0)
	v_mfma_f32_16x16x32_bf16 v[124:127], v[144:147], v[168:171], v[124:127]
	ds_read_b128 v[184:187], v143 offset:33792
	v_mfma_f32_16x16x32_bf16 v[120:123], v[160:163], v[168:171], v[120:123]
	ds_read_b128 v[192:195], v143 offset:35840
	v_mfma_f32_16x16x32_bf16 v[116:119], v[144:147], v[188:191], v[116:119]
	ds_read_b128 v[200:203], v143 offset:37888
	v_mfma_f32_16x16x32_bf16 v[112:115], v[160:163], v[188:191], v[112:115]
	ds_read_b128 v[208:211], v143 offset:39936
	v_mfma_f32_16x16x32_bf16 v[100:103], v[144:147], v[196:199], v[100:103]
	v_mfma_f32_16x16x32_bf16 v[96:99], v[160:163], v[196:199], v[96:99]
	v_mfma_f32_16x16x32_bf16 v[84:87], v[144:147], v[204:207], v[84:87]
	v_mfma_f32_16x16x32_bf16 v[80:83], v[160:163], v[204:207], v[80:83]
	s_waitcnt lgkmcnt(0)
	v_mfma_f32_16x16x32_bf16 v[124:127], v[148:151], v[184:187], v[124:127]
	v_mfma_f32_16x16x32_bf16 v[120:123], v[164:167], v[184:187], v[120:123]
	v_mfma_f32_16x16x32_bf16 v[116:119], v[148:151], v[192:195], v[116:119]
	v_mfma_f32_16x16x32_bf16 v[112:115], v[164:167], v[192:195], v[112:115]
	v_mfma_f32_16x16x32_bf16 v[100:103], v[148:151], v[200:203], v[100:103]
	v_mfma_f32_16x16x32_bf16 v[96:99], v[164:167], v[200:203], v[96:99]
	v_mfma_f32_16x16x32_bf16 v[84:87], v[148:151], v[208:211], v[84:87]
	v_mfma_f32_16x16x32_bf16 v[80:83], v[164:167], v[208:211], v[80:83]
	s_barrier
	s_setprio 0
	s_add_i32 s17, 0, 0x1c000
	s_add_i32 s1, s1, s85
	v_add_u32_e32 v183, s17, v141
	v_lshl_add_u64 v[152:153], v[152:153], 0, s[8:9]
	s_mov_b32 m0, s1
	ds_read_b128 v[212:215], v183
	ds_read_b128 v[216:219], v183 offset:1024
	ds_read_b128 v[220:223], v183 offset:2048
	ds_read_b128 v[224:227], v183 offset:3072
	global_load_lds_dwordx4 v[152:153], off
	v_lshl_add_u64 v[152:153], v[228:229], 0, s[8:9]
	s_add_i32 m0, s1, 0x2000
	s_nop 0
	global_load_lds_dwordx4 v[152:153], off
	s_setprio 1
	s_barrier
	s_waitcnt lgkmcnt(0)
	v_mfma_f32_16x16x32_bf16 v[108:111], v[212:215], v[168:171], v[108:111]
	v_mfma_f32_16x16x32_bf16 v[104:107], v[220:223], v[168:171], v[104:107]
	v_mfma_f32_16x16x32_bf16 v[92:95], v[212:215], v[188:191], v[92:95]
	v_mfma_f32_16x16x32_bf16 v[88:91], v[220:223], v[188:191], v[88:91]
	v_mfma_f32_16x16x32_bf16 v[76:79], v[212:215], v[196:199], v[76:79]
	v_mfma_f32_16x16x32_bf16 v[72:75], v[220:223], v[196:199], v[72:75]
	s_mov_b32 m0, s92
	v_mfma_f32_16x16x32_bf16 v[68:71], v[212:215], v[204:207], v[68:71]
	v_lshl_add_u64 v[152:153], v[230:231], 0, s[8:9]
	v_mfma_f32_16x16x32_bf16 v[64:67], v[220:223], v[204:207], v[64:67]
	v_mfma_f32_16x16x32_bf16 v[108:111], v[216:219], v[184:187], v[108:111]
	v_mfma_f32_16x16x32_bf16 v[104:107], v[224:227], v[184:187], v[104:107]
	v_mfma_f32_16x16x32_bf16 v[92:95], v[216:219], v[192:195], v[92:95]
	v_mfma_f32_16x16x32_bf16 v[88:91], v[224:227], v[192:195], v[88:91]
	v_mfma_f32_16x16x32_bf16 v[76:79], v[216:219], v[200:203], v[76:79]
	v_mfma_f32_16x16x32_bf16 v[72:75], v[224:227], v[200:203], v[72:75]
	v_mfma_f32_16x16x32_bf16 v[68:71], v[216:219], v[208:211], v[68:71]
	v_mfma_f32_16x16x32_bf16 v[64:67], v[224:227], v[208:211], v[64:67]
	s_barrier
	s_setprio 0
	ds_read_b128 v[168:171], v143 offset:49152
	ds_read_b128 v[184:187], v143 offset:50176
	ds_read_b128 v[188:191], v143 offset:51200
	ds_read_b128 v[192:195], v143 offset:52224
	ds_read_b128 v[196:199], v143 offset:53248
	ds_read_b128 v[200:203], v143 offset:54272
	ds_read_b128 v[204:207], v143 offset:55296
	ds_read_b128 v[208:211], v143 offset:56320
	global_load_lds_dwordx4 v[152:153], off
	v_lshl_add_u64 v[152:153], v[232:233], 0, s[8:9]
	s_mov_b32 m0, s93
	s_nop 0
	global_load_lds_dwordx4 v[152:153], off
	s_setprio 1
	s_barrier
	s_waitcnt lgkmcnt(0)
	v_mfma_f32_16x16x32_bf16 v[60:63], v[144:147], v[168:171], v[60:63]
	v_mfma_f32_16x16x32_bf16 v[56:59], v[160:163], v[168:171], v[56:59]
	v_mfma_f32_16x16x32_bf16 v[52:55], v[144:147], v[188:191], v[52:55]
	v_mfma_f32_16x16x32_bf16 v[48:51], v[160:163], v[188:191], v[48:51]
	v_mfma_f32_16x16x32_bf16 v[36:39], v[144:147], v[196:199], v[36:39]
	v_mfma_f32_16x16x32_bf16 v[32:35], v[160:163], v[196:199], v[32:35]
	v_mfma_f32_16x16x32_bf16 v[20:23], v[144:147], v[204:207], v[20:23]
	v_mfma_f32_16x16x32_bf16 v[16:19], v[160:163], v[204:207], v[16:19]
	v_mfma_f32_16x16x32_bf16 v[60:63], v[148:151], v[184:187], v[60:63]
	v_mfma_f32_16x16x32_bf16 v[56:59], v[164:167], v[184:187], v[56:59]
	v_mfma_f32_16x16x32_bf16 v[52:55], v[148:151], v[192:195], v[52:55]
	v_mfma_f32_16x16x32_bf16 v[48:51], v[164:167], v[192:195], v[48:51]
	v_mfma_f32_16x16x32_bf16 v[36:39], v[148:151], v[200:203], v[36:39]
	v_mfma_f32_16x16x32_bf16 v[32:35], v[164:167], v[200:203], v[32:35]
	v_mfma_f32_16x16x32_bf16 v[20:23], v[148:151], v[208:211], v[20:23]
	v_mfma_f32_16x16x32_bf16 v[16:19], v[164:167], v[208:211], v[16:19]
	s_barrier
	s_setprio 0
	s_add_i32 s1, s17, s85
	v_lshl_add_u64 v[144:145], v[234:235], 0, s[8:9]
	s_mov_b32 m0, s1
	s_nop 0
	global_load_lds_dwordx4 v[144:145], off
	v_lshl_add_u64 v[144:145], v[236:237], 0, s[8:9]
	s_add_i32 m0, s1, 0x2000
	s_nop 0
	global_load_lds_dwordx4 v[144:145], off
	s_waitcnt vmcnt(6)
	s_setprio 1
	s_barrier
	v_mfma_f32_16x16x32_bf16 v[44:47], v[212:215], v[168:171], v[44:47]
	v_mfma_f32_16x16x32_bf16 v[40:43], v[220:223], v[168:171], v[40:43]
	v_mfma_f32_16x16x32_bf16 v[28:31], v[212:215], v[188:191], v[28:31]
	v_mfma_f32_16x16x32_bf16 v[24:27], v[220:223], v[188:191], v[24:27]
	v_mfma_f32_16x16x32_bf16 v[12:15], v[212:215], v[196:199], v[12:15]
	v_mfma_f32_16x16x32_bf16 v[8:11], v[220:223], v[196:199], v[8:11]
	s_add_u32 vcc_lo, vcc_lo, 0x100
	v_mfma_f32_16x16x32_bf16 v[4:7], v[212:215], v[204:207], v[4:7]
	s_addc_u32 vcc_hi, vcc_hi, 0
	v_mfma_f32_16x16x32_bf16 v[0:3], v[220:223], v[204:207], v[0:3]
	s_add_u32 s96, s96, 0x100
	v_mfma_f32_16x16x32_bf16 v[44:47], v[216:219], v[184:187], v[44:47]
	s_addc_u32 s65, s65, 0
	v_mfma_f32_16x16x32_bf16 v[40:43], v[224:227], v[184:187], v[40:43]
	s_cmp_ge_u32 s0, s94
	v_mfma_f32_16x16x32_bf16 v[28:31], v[216:219], v[192:195], v[28:31]
	s_mov_b32 s34, s0
	v_mfma_f32_16x16x32_bf16 v[24:27], v[224:227], v[192:195], v[24:27]
	v_mfma_f32_16x16x32_bf16 v[12:15], v[216:219], v[200:203], v[12:15]
	v_mfma_f32_16x16x32_bf16 v[8:11], v[224:227], v[200:203], v[8:11]
	v_mfma_f32_16x16x32_bf16 v[4:7], v[216:219], v[208:211], v[4:7]
	v_mfma_f32_16x16x32_bf16 v[0:3], v[224:227], v[208:211], v[0:3]
	s_cbranch_scc1 .Lx_nobar_plain
	s_barrier
	s_setprio 0
	s_branch .LBB0_100
;     __device__ __forceinline__ void operator()(const f32x4 (&acc)[2][2][4][2], const Unit& u, int wr, int wc, int fr, int fq) const {
;         const int row0 = u.pm * BM + wr * 64 + fr, col0 = u.pn * BM + wc * 32 + 8 * fq;
; #pragma unroll
;         for (int ai = 0; ai < 2; ++ai)
; #pragma unroll
;             for (int m = 0; m < 4; ++m) { bf16_t* rowp = O + (size_t)(row0 + ai * HALF + m * 16) * ldc + col0;
; #pragma unroll
;                 for (int bj = 0; bj < 2; ++bj) { const f32x4 v0 = acc[ai][bj][m][0], v1 = acc[ai][bj][m][1];
;                     u32x4 w; w.x = cvt_pk_bf16(v0[0], v0[1]); w.y = cvt_pk_bf16(v0[2], v0[3]); w.z = cvt_pk_bf16(v1[0], v1[1]); w.w = cvt_pk_bf16(v1[2], v1[3]);
;                     *(u32x4*)(rowp + bj * HALF) = w; } }
; template <class Epi, class Sched>
; __device__ __forceinline__ void gemm_phase(LAS unsigned char* lds, const Gemm g, const Sched& S, const Epi& E, int tid) {
;     ...
;         E(acc, cur, wr, wc, fr, fq);
;         if (!has_next) break;
; #pragma unroll
;         for (int a = 0; a < 2; ++a)
; #pragma unroll
;             for (int b = 0; b < 2; ++b)
; #pragma unroll
;                 for (int m = 0; m < 4; ++m)
; #pragma unroll
;                     for (int n = 0; n < 2; ++n) acc[a][b][m][n] = (f32x4){0.f, 0.f, 0.f, 0.f};
;         cur = nxt; cA = nA; cB = nB; ++ui;
.Lx_nobar_plain:
	s_setprio 0
	s_cmp_lg_u32 s100, 0
	s_cbranch_scc1 .Lx_skip1_plain
	s_barrier
.Lx_skip1_plain:
	v_lshl_add_u32 v148, s60, 8, v140
	v_lshl_or_b32 v144, s61, 8, v142
	v_ashrrev_i32_e32 v145, 31, v144
	v_mad_i64_i32 v[146:147], s[0:1], v148, s74, 0
	v_cvt_pk_bf16_f32 v108, v108, v109
	v_cvt_pk_bf16_f32 v109, v110, v111
	v_cvt_pk_bf16_f32 v110, v104, v105
	v_or_b32_e32 v104, 16, v148
	v_lshl_add_u64 v[146:147], v[146:147], 1, s[14:15]
	v_lshlrev_b64 v[144:145], 1, v[144:145]
	v_mad_i64_i32 v[104:105], s[0:1], v104, s74, 0
	v_cvt_pk_bf16_f32 v92, v92, v93
	v_cvt_pk_bf16_f32 v93, v94, v95
	v_cvt_pk_bf16_f32 v94, v88, v89
	v_or_b32_e32 v88, 32, v148
	v_lshl_add_u64 v[146:147], v[146:147], 0, v[144:145]
	v_cvt_pk_bf16_f32 v111, v106, v107
	v_lshl_add_u64 v[104:105], v[104:105], 1, s[14:15]
	v_mad_i64_i32 v[88:89], s[0:1], v88, s74, 0
	v_cvt_pk_bf16_f32 v76, v76, v77
	v_cvt_pk_bf16_f32 v77, v78, v79
	v_cvt_pk_bf16_f32 v78, v72, v73
	v_or_b32_e32 v72, 48, v148
	v_cvt_pk_bf16_f32 v68, v68, v69
	v_cvt_pk_bf16_f32 v69, v70, v71
	v_cvt_pk_bf16_f32 v70, v64, v65
	v_add_u32_e32 v64, 0x80, v148
	v_cvt_pk_bf16_f32 v124, v124, v125
	v_cvt_pk_bf16_f32 v125, v126, v127
	v_cvt_pk_bf16_f32 v126, v120, v121
	v_cvt_pk_bf16_f32 v127, v122, v123
	global_store_dwordx4 v[146:147], v[108:111], off offset:256
	v_cvt_pk_bf16_f32 v95, v90, v91
	v_lshl_add_u64 v[88:89], v[88:89], 1, s[14:15]
	v_lshl_add_u64 v[108:109], v[104:105], 0, v[144:145]
	v_mad_i64_i32 v[72:73], s[0:1], v72, s74, 0
	v_mad_i64_i32 v[64:65], s[0:1], v64, s74, 0
	v_cvt_pk_bf16_f32 v44, v44, v45
	v_cvt_pk_bf16_f32 v45, v46, v47
	v_cvt_pk_bf16_f32 v46, v40, v41
	v_add_u32_e32 v40, 0x90, v148
	global_store_dwordx4 v[146:147], v[124:127], off
	v_cvt_pk_bf16_f32 v104, v116, v117
	v_cvt_pk_bf16_f32 v105, v118, v119
	v_cvt_pk_bf16_f32 v106, v112, v113
	v_cvt_pk_bf16_f32 v107, v114, v115
	global_store_dwordx4 v[108:109], v[92:95], off offset:256
	v_cvt_pk_bf16_f32 v79, v74, v75
	v_lshl_add_u64 v[72:73], v[72:73], 1, s[14:15]
	v_lshl_add_u64 v[92:93], v[88:89], 0, v[144:145]
	v_lshl_add_u64 v[64:65], v[64:65], 1, s[14:15]
	v_mad_i64_i32 v[40:41], s[0:1], v40, s74, 0
	v_cvt_pk_bf16_f32 v28, v28, v29
	v_cvt_pk_bf16_f32 v29, v30, v31
	v_cvt_pk_bf16_f32 v30, v24, v25
	v_add_u32_e32 v24, 0xa0, v148
	global_store_dwordx4 v[108:109], v[104:107], off
	v_cvt_pk_bf16_f32 v88, v100, v101
	v_cvt_pk_bf16_f32 v89, v102, v103
	v_cvt_pk_bf16_f32 v90, v96, v97
	v_cvt_pk_bf16_f32 v91, v98, v99
	global_store_dwordx4 v[92:93], v[76:79], off offset:256
	v_cvt_pk_bf16_f32 v74, v80, v81
	v_cvt_pk_bf16_f32 v75, v82, v83
	v_lshl_add_u64 v[76:77], v[72:73], 0, v[144:145]
	v_cvt_pk_bf16_f32 v72, v84, v85
	v_cvt_pk_bf16_f32 v73, v86, v87
	v_cvt_pk_bf16_f32 v71, v66, v67
	v_lshl_add_u64 v[64:65], v[64:65], 0, v[144:145]
	v_cvt_pk_bf16_f32 v47, v42, v43
	v_lshl_add_u64 v[40:41], v[40:41], 1, s[14:15]
	v_mad_i64_i32 v[24:25], s[0:1], v24, s74, 0
	v_cvt_pk_bf16_f32 v12, v12, v13
	v_cvt_pk_bf16_f32 v13, v14, v15
	v_cvt_pk_bf16_f32 v14, v8, v9
	v_add_u32_e32 v8, 0xb0, v148
	global_store_dwordx4 v[92:93], v[88:91], off
	global_store_dwordx4 v[76:77], v[72:75], off
	global_store_dwordx4 v[76:77], v[68:71], off offset:256
	v_cvt_pk_bf16_f32 v60, v60, v61
	v_cvt_pk_bf16_f32 v61, v62, v63
	v_cvt_pk_bf16_f32 v62, v56, v57
	v_cvt_pk_bf16_f32 v63, v58, v59
	global_store_dwordx4 v[64:65], v[44:47], off offset:256
	v_cvt_pk_bf16_f32 v31, v26, v27
	v_lshl_add_u64 v[24:25], v[24:25], 1, s[14:15]
	v_lshl_add_u64 v[44:45], v[40:41], 0, v[144:145]
	v_mad_i64_i32 v[8:9], s[0:1], v8, s74, 0
	global_store_dwordx4 v[64:65], v[60:63], off
	v_cvt_pk_bf16_f32 v40, v52, v53
	v_cvt_pk_bf16_f32 v41, v54, v55
	v_cvt_pk_bf16_f32 v42, v48, v49
	v_cvt_pk_bf16_f32 v43, v50, v51
	global_store_dwordx4 v[44:45], v[28:31], off offset:256
	v_cvt_pk_bf16_f32 v15, v10, v11
	v_lshl_add_u64 v[8:9], v[8:9], 1, s[14:15]
	v_lshl_add_u64 v[28:29], v[24:25], 0, v[144:145]
	global_store_dwordx4 v[44:45], v[40:43], off
	v_cvt_pk_bf16_f32 v24, v36, v37
	v_cvt_pk_bf16_f32 v25, v38, v39
	v_cvt_pk_bf16_f32 v26, v32, v33
	v_cvt_pk_bf16_f32 v27, v34, v35
	global_store_dwordx4 v[28:29], v[12:15], off offset:256
	v_cvt_pk_bf16_f32 v10, v16, v17
	v_cvt_pk_bf16_f32 v11, v18, v19
	v_lshl_add_u64 v[12:13], v[8:9], 0, v[144:145]
	v_cvt_pk_bf16_f32 v8, v20, v21
	v_cvt_pk_bf16_f32 v9, v22, v23
	v_cvt_pk_bf16_f32 v4, v4, v5
	v_cvt_pk_bf16_f32 v5, v6, v7
	v_cvt_pk_bf16_f32 v6, v0, v1
	v_cvt_pk_bf16_f32 v7, v2, v3
	s_and_b64 vcc, exec, s[36:37]
	s_mov_b32 s61, s63
	s_mov_b32 s60, s58
	s_mov_b64 s[34:35], s[40:41]
	s_mov_b64 s[44:45], s[38:39]
	global_store_dwordx4 v[28:29], v[24:27], off
	global_store_dwordx4 v[12:13], v[8:11], off
	global_store_dwordx4 v[12:13], v[4:7], off offset:256
	s_cmp_lg_u32 s100, 0
	s_cbranch_scc0 .Lx_skip2_plain
	s_barrier
.Lx_skip2_plain:
	s_cbranch_vccz .LBB0_89
	s_waitcnt vmcnt(0)
	s_cmpk_gt_u32 s76, 0xff
	s_cbranch_scc1 .LBB0_68
	s_barrier
	s_branch .LBB0_68

; #define PG8_BAR __builtin_amdgcn_s_barrier()
; #define tid fresh_tid(wave_s)
;     __device__ bool next(int i, Unit& u) const {
;         const long L = (long)i * G + c; if (L >= nwg) return false;
;         int wgid = (int)L; { const int q = nwg / NXCD, r = nwg % NXCD, xcd = wgid % NXCD, off = wgid / NXCD; wgid = (xcd < r ? xcd * (q + 1) : r * (q + 1) + (xcd - r) * q) + off; }
;         const int nig = WGM * nN, gid = wgid / nig, fm = gid * WGM, gsz = (nM - fm) < WGM ? (nM - fm) : WGM;
;         u.pm = fm + ((wgid % nig) % gsz); u.pn = (wgid % nig) / gsz; return true;
; template <class Epi, class Sched>
; __device__ __forceinline__ void gemm_phase(LAS unsigned char* lds, const Gemm g, const Sched& S, const Epi& E, int tid) {
;     const int wid = __builtin_amdgcn_readfirstlane(tid >> 6), lane = tid & 63, wr = wid >> 2, wc = wid & 3, fr = lane & 15, fq = lane >> 4;
;     const int K = g.K, nt = K / BK;
;     unsigned voffA[2], voffB[2];
; #pragma unroll
;     for (int i = 0; i < 2; ++i) { int R, C; stage_rc(tid * 16 + i * 8192, R, C); const int Rb = Epi::PERM ? ((R & ~31) + perm32(R & 31)) : R;
;         voffA[i] = (unsigned)(R * K + C) * 2u; voffB[i] = (unsigned)(Rb * K + C) * 2u; }
;     const size_t kstep = (size_t)(BK * 2);
;     const size_t hstep = (size_t)HALF * K * 2;
;     const size_t tstep = 2 * hstep;
;     const unsigned ldsw = (unsigned)wid * 1024u;
;     const int aoff = lds_byte(wr * 64 + fr, fq * 8), boff = lds_byte(wc * 32 + fr, fq * 8);
;     ...
;     Unit cur, nxt; int ui = 0;
;     if (!S.next(0, cur)) return;
;     f32x4 acc[2][2][4][2];
; #pragma unroll
;     for (int a = 0; a < 2; ++a)
; #pragma unroll
;         for (int b = 0; b < 2; ++b)
; #pragma unroll
;             for (int m = 0; m < 4; ++m)
; #pragma unroll
;                 for (int n = 0; n < 2; ++n) acc[a][b][m][n] = (f32x4){0.f, 0.f, 0.f, 0.f};
;     bf16x8 At[4][2], B0[2][2], B1[2][2];
;     const char* cA = (const char*)g.A + (size_t)cur.pm * tstep; const char* cB = (const char*)g.Bt + (size_t)cur.pn * tstep;
;     PG8_STAGE(PG8_SB(0, 0), cB, voffB); PG8_STAGE(PG8_SA(0, 0), cA, voffA); PG8_STAGE(PG8_SB(0, 1), cB + hstep, voffB); PG8_STAGE(PG8_SA(0, 1), cA + hstep, voffA);
;     if (wr == 1) PG8_BAR;
.LBB0_105:
	v_readlane_b32 s0, v244, 36
	s_lshr_b32 s65, s0, 4
	s_cmp_lt_i32 s16, 2
	s_mov_b64 s[14:15], -1
	s_cbranch_scc1 .LBB0_192
	s_cmp_lt_i32 s16, 5
	v_readlane_b32 s55, v244, 9
	s_cbranch_scc1 .LBB0_121
	s_cmp_eq_u32 s16, 5
	s_cbranch_scc0 .LBB0_120
	v_mov_b32_e32 v14, v173
	s_cmpk_gt_i32 s69, 0xaff
	v_readfirstlane_b32 s18, v14
	s_cbranch_scc1 .LBB0_120
	v_lshlrev_b32_e32 v0, 4, v14
	v_add_u32_e32 v1, 0x2000, v0
	v_ashrrev_i32_e32 v2, 31, v1
	v_lshrrev_b32_e32 v2, 22, v2
	v_add_u32_e32 v2, v1, v2
	v_ashrrev_i32_e32 v8, 10, v2
	v_mul_i32_i24_e32 v2, 0x400, v8
	v_sub_u32_e32 v1, v1, v2
	v_lshrrev_b32_e32 v2, 4, v1
	v_bitop3_b32 v1, v2, v1, 32 bitop3:0x6c
	v_ashrrev_i32_e32 v2, 31, v1
	v_lshrrev_b32_e32 v2, 26, v2
	v_add_u32_e32 v2, v1, v2
	v_lshlrev_b32_e32 v3, 3, v8
	v_ashrrev_i32_e32 v9, 6, v2
	v_and_b32_e32 v3, -16, v3
	v_add_u32_e32 v3, v9, v3
	v_and_b32_e32 v4, 3, v9
	s_mov_b32 s6, 0x1fffe0
	v_lshrrev_b32_e32 v5, 2, v3
	v_lshlrev_b32_e32 v6, 1, v3
	v_and_b32_e32 v2, 0xc0, v2
	v_and_or_b32 v4, v3, s6, v4
	v_and_b32_e32 v5, 4, v5
	v_and_b32_e32 v6, 24, v6
	v_sub_u32_e32 v1, v1, v2
	v_or3_b32 v4, v4, v5, v6
	v_lshlrev_b32_e32 v5, 5, v8
	v_ashrrev_i16_sdwa v1, v178, sext(v1) dst_sel:DWORD dst_unused:UNUSED_PAD src0_sel:DWORD src1_sel:BYTE_0
	v_and_b32_e32 v5, 32, v5
	v_bfe_i32 v10, v1, 0, 16
	v_add_lshl_u32 v1, v5, v10, 1
	v_lshl_add_u32 v128, v4, 11, v1
	v_lshl_add_u32 v130, v3, 11, v1
	v_bfe_i32 v1, v14, 27, 1
	v_lshrrev_b32_e32 v1, 22, v1
	v_add_u32_e32 v1, v0, v1
	v_and_b32_e32 v1, 0xfffffc00, v1
	v_sub_u32_e32 v0, v0, v1
	v_lshrrev_b32_e32 v1, 4, v0
	v_bitop3_b32 v1, v1, v0, 32 bitop3:0x6c
	v_ashrrev_i32_e32 v0, 31, v0
	v_lshrrev_b32_e32 v0, 26, v0
	v_add_u32_e32 v0, v1, v0
	v_ashrrev_i32_e32 v11, 6, v0
	v_ashrrev_i32_e32 v0, 31, v14
	v_lshrrev_b32_e32 v0, 26, v0
	v_add_u32_e32 v0, v14, v0
	v_ashrrev_i32_e32 v12, 6, v0
	v_lshlrev_b32_e32 v0, 3, v12
	s_add_u32 s19, s26, 0x15880000
	v_and_b32_e32 v0, -16, v0
	s_addc_u32 s44, s27, 0
	v_add_u32_e32 v0, v11, v0
	v_and_b32_e32 v2, 3, v11
	s_ashr_i32 s46, s69, 31
	v_and_or_b32 v2, v0, s6, v2
	s_lshr_b32 s6, s46, 29
	s_add_i32 s6, s69, s6
	s_ashr_i32 s0, s18, 6
	s_ashr_i32 s14, s6, 3
	s_and_b32 s6, s6, -8
	s_ashr_i32 s1, s18, 8
	s_ashr_i32 s100, s18, 8
	s_lshl_b32 s45, s0, 10
	s_sub_i32 s6, s69, s6
	s_cmp_lt_i32 s6, 0
	s_movk_i32 s15, 0x161
	s_cselect_b32 s15, s15, 0x160
	s_mul_i32 s6, s6, s15
	s_add_i32 s6, s6, s14
	s_mul_hi_i32 s14, s6, 0x2e8ba2e9
	s_lshr_b32 s15, s14, 31
	s_ashr_i32 s14, s14, 5
	s_add_i32 s14, s14, s15
	s_lshl_b32 s15, s14, 3
	s_mulk_i32 s14, 0xb0
	s_sub_i32 s14, s6, s14
	s_bfe_u32 s6, s14, 0x3001c
	s_add_i32 s17, s14, s6
	s_sext_i32_i16 s6, s17
	s_and_b32 s17, s17, 0xfff8
	v_lshrrev_b32_e32 v3, 2, v0
	v_lshlrev_b32_e32 v4, 1, v0
	s_sub_i32 s14, s14, s17
	v_and_b32_e32 v3, 4, v3
	v_and_b32_e32 v4, 24, v4
	s_sext_i32_i16 s14, s14
	v_or3_b32 v2, v2, v3, v4
	v_mul_i32_i24_e32 v4, 64, v11
	s_lshr_b32 s6, s6, 3
	s_add_i32 s38, s15, s14
	v_sub_u32_e32 v1, v1, v4
	s_ashr_i32 s39, s38, 31
	s_bfe_i64 s[22:23], s[6:7], 0x100000
	v_lshlrev_b32_e32 v3, 5, v12
	v_ashrrev_i16_sdwa v1, v178, sext(v1) dst_sel:DWORD dst_unused:UNUSED_PAD src0_sel:DWORD src1_sel:BYTE_0
	s_lshl_b64 s[14:15], s[38:39], 19
	s_lshl_b64 s[22:23], s[22:23], 19
	v_and_b32_e32 v3, 32, v3
	v_bfe_i32 v13, v1, 0, 16
	s_add_u32 s42, s19, s22
	v_add_lshl_u32 v1, v3, v13, 1
	s_addc_u32 s43, s44, s23
	s_add_i32 s39, s45, 0
	v_lshl_add_u32 v154, v2, 11, v1
	s_add_i32 m0, s39, 0x10000
	v_lshl_add_u32 v132, v0, 11, v1
	global_load_lds_dwordx4 v154, s[42:43]
	s_add_i32 m0, s39, 0x12000
	s_add_u32 s40, s26, s14
	global_load_lds_dwordx4 v128, s[42:43]
	s_addc_u32 s41, s27, s15
	s_mov_b32 m0, s39
	s_add_i32 s47, s39, 0x2000
	global_load_lds_dwordx4 v132, s[40:41]
	s_mov_b32 m0, s47
	s_add_u32 s14, s42, 0x40000
	global_load_lds_dwordx4 v130, s[40:41]
	s_addc_u32 s15, s43, 0
	s_add_i32 m0, s39, 0x14000
	v_mov_b32_e32 v129, v155
	global_load_lds_dwordx4 v154, s[14:15]
	s_add_i32 m0, s39, 0x16000
	v_mov_b32_e32 v133, v155
	global_load_lds_dwordx4 v128, s[14:15]
	s_add_u32 s14, s40, 0x40000
	s_addc_u32 s15, s41, 0
	s_add_i32 s48, s39, 0x4000
	s_mov_b32 m0, s48
	s_add_i32 s49, s39, 0x6000
	global_load_lds_dwordx4 v132, s[14:15]
	s_mov_b32 m0, s49
	v_mov_b32_e32 v131, v155
	global_load_lds_dwordx4 v130, s[14:15]
	v_lshl_add_u64 v[6:7], s[42:43], 0, v[154:155]
	v_lshl_add_u64 v[4:5], s[42:43], 0, v[128:129]
	v_lshl_add_u64 v[2:3], s[40:41], 0, v[132:133]
	s_cmp_lg_u32 s1, 1
	v_lshl_add_u64 v[0:1], s[40:41], 0, v[130:131]
	s_cbranch_scc1 .LBB0_111
	s_barrier

; #define PG8_STAGE(bufoff, gbase, voff) do { _Pragma("unroll") for (int _i = 0; _i < 2; ++_i) \
;         __builtin_amdgcn_global_load_lds((const unsigned*)((const char*)(gbase) + (voff)[_i]), (LAS unsigned*)(lds + (bufoff) + ldsw + _i * 8192), 16, 0, 0); } while (0)
; #define PG8_LDA(dst, b, h) do { _Pragma("unroll") for (int m = 0; m < 4; ++m) _Pragma("unroll") for (int k = 0; k < 2; ++k) dst[m][k] = *(const LAS bf16x8*)(lds + PG8_SA(b, h) + aoff + m * 2048 + k * 1024); } while (0)
; #define PG8_LDB(dst, b, h) do { _Pragma("unroll") for (int n = 0; n < 2; ++n) _Pragma("unroll") for (int k = 0; k < 2; ++k) dst[n][k] = *(const LAS bf16x8*)(lds + PG8_SB(b, h) + boff + n * 2048 + k * 1024); } while (0)
; #define PG8_WAIT_V(n) asm volatile("s_waitcnt vmcnt(" #n ")" ::: "memory")
; #define PG8_WAIT_L(n) asm volatile("s_waitcnt lgkmcnt(" #n ")" ::: "memory")
; #define PG8_BAR __builtin_amdgcn_s_barrier()
; #define PG8_SCHED __builtin_amdgcn_sched_barrier(0)
; template <class Epi, class Sched>
; __device__ __forceinline__ void gemm_phase(LAS unsigned char* lds, const Gemm g, const Sched& S, const Epi& E, int tid) {
;     ...
;         const bool has_next = S.next(ui + 1, nxt);
;         const char* nA = has_next ? (const char*)g.A + (size_t)nxt.pm * tstep : cA; const char* nB = has_next ? (const char*)g.Bt + (size_t)nxt.pn * tstep : cB;
;         for (int t = 0; t < nt; t += 2) {
;             const bool last = (t == nt - 2);
;             const char* a1 = cA + (size_t)(t + 1) * kstep;
;             const char* a2 = last ? nA : cA + (size_t)(t + 2) * kstep; const char* b2 = last ? nB : cB + (size_t)(t + 2) * kstep;
;             const char* a3 = a2 + kstep; const char* b3 = b2 + kstep;
;             PG8_LDB(B0, 0, 0); PG8_SCHED; PG8_LDA(At, 0, 0); PG8_STAGE(PG8_SA(1, 1), a1 + hstep, voffA);
;             PG8_WAIT_L(8); PG8_BAR; PG8_WAIT_L(0); PG8_MMA(0, 0, At, B0); PG8_BAR; PG8_SCHED;
;             PG8_LDB(B1, 0, 1); PG8_STAGE(PG8_SB(0, 0), b2, voffB);
;             PG8_BAR; PG8_WAIT_L(0); PG8_MMA(0, 1, At, B1); PG8_BAR;
;             PG8_LDA(At, 0, 1); PG8_STAGE(PG8_SA(0, 0), a2, voffA);
;             PG8_BAR; PG8_WAIT_L(0); PG8_MMA(1, 0, At, B0); PG8_BAR; PG8_SCHED;
;             PG8_STAGE(PG8_SB(0, 1), b2 + hstep, voffB);
;             PG8_WAIT_V(6); PG8_BAR; PG8_MMA(1, 1, At, B1); PG8_BAR;
.LBB0_114:
	s_ashr_i32 s25, s24, 31
	s_lshl_b64 s[0:1], s[24:25], 19
	v_cmp_lt_i64_e32 vcc, s[28:29], v[158:159]
	s_add_u32 s28, s26, s0
	s_addc_u32 s29, s27, s1
	s_and_b64 s[0:1], vcc, exec
	s_cselect_b32 s25, s29, s41
	s_cselect_b32 s53, s28, s40
	s_ashr_i32 s15, s14, 31
	s_lshl_b64 s[0:1], s[14:15], 19
	s_add_u32 s30, s19, s0
	s_addc_u32 s31, s44, s1
	s_and_b64 s[0:1], vcc, exec
	s_cselect_b32 s15, s31, s43
	s_cselect_b32 s55, s30, s42
	s_add_u32 s40, s40, 0x40080
	s_addc_u32 s41, s41, 0
	s_add_u32 s58, s42, 0x100
	s_addc_u32 s60, s43, 0
	s_mov_b32 s61, -2
	s_add_u32 s0, s40, 0xfffc0080
	s_addc_u32 s1, s41, -1
	s_add_i32 s17, 0, 0x10000
	v_add_u32_e32 v160, s17, v143
	ds_read_b128 v[138:141], v160
	ds_read_b128 v[146:149], v160 offset:1024
	ds_read_b128 v[150:153], v160 offset:2048
	ds_read_b128 v[160:163], v160 offset:3072
	s_cmp_eq_u32 s61, 12
	s_cselect_b32 s43, s25, s1
	s_cselect_b32 s42, s53, s0
	s_cselect_b32 s35, s15, s60
	s_cselect_b32 s34, s55, s58
	v_lshl_add_u64 v[208:209], s[40:41], 0, v[134:135]
	s_add_i32 m0, s39, 0xc000
	ds_read_b128 v[164:167], v145
	ds_read_b128 v[184:187], v145 offset:2048
	ds_read_b128 v[192:195], v145 offset:4096
	ds_read_b128 v[200:203], v145 offset:6144
	global_load_lds_dwordx4 v[208:209], off
	v_lshl_add_u64 v[208:209], s[40:41], 0, v[136:137]
	s_add_i32 m0, s39, 0xe000
	s_nop 0
	global_load_lds_dwordx4 v[208:209], off
	s_waitcnt lgkmcnt(4)
	s_setprio 1
	s_barrier
	s_waitcnt lgkmcnt(0)
	v_mfma_f32_16x16x32_bf16 v[124:127], v[138:141], v[164:167], 0
	ds_read_b128 v[168:171], v145 offset:1024
	v_mfma_f32_16x16x32_bf16 v[120:123], v[150:153], v[164:167], 0
	ds_read_b128 v[188:191], v145 offset:3072
	v_mfma_f32_16x16x32_bf16 v[108:111], v[138:141], v[184:187], 0
	ds_read_b128 v[196:199], v145 offset:5120
	v_mfma_f32_16x16x32_bf16 v[104:107], v[150:153], v[184:187], 0
	ds_read_b128 v[204:207], v145 offset:7168
	v_mfma_f32_16x16x32_bf16 v[92:95], v[138:141], v[192:195], 0
	v_mfma_f32_16x16x32_bf16 v[88:91], v[150:153], v[192:195], 0
	v_mfma_f32_16x16x32_bf16 v[76:79], v[138:141], v[200:203], 0
	v_mfma_f32_16x16x32_bf16 v[72:75], v[150:153], v[200:203], 0
	s_waitcnt lgkmcnt(0)
	v_mfma_f32_16x16x32_bf16 v[124:127], v[146:149], v[168:171], v[124:127]
	v_mfma_f32_16x16x32_bf16 v[120:123], v[160:163], v[168:171], v[120:123]
	v_mfma_f32_16x16x32_bf16 v[108:111], v[146:149], v[188:191], v[108:111]
	v_mfma_f32_16x16x32_bf16 v[104:107], v[160:163], v[188:191], v[104:107]
	v_mfma_f32_16x16x32_bf16 v[92:95], v[146:149], v[196:199], v[92:95]
	v_mfma_f32_16x16x32_bf16 v[88:91], v[160:163], v[196:199], v[88:91]
	v_mfma_f32_16x16x32_bf16 v[76:79], v[146:149], v[204:207], v[76:79]
	v_mfma_f32_16x16x32_bf16 v[72:75], v[160:163], v[204:207], v[72:75]
	s_barrier
	s_setprio 0
	s_add_i32 s63, 0, 0x14000
	s_add_i32 s0, s17, s45
	v_add_u32_e32 v183, s63, v143
	v_lshl_add_u64 v[224:225], s[34:35], 0, v[154:155]
	s_mov_b32 m0, s0
	ds_read_b128 v[208:211], v183
	ds_read_b128 v[212:215], v183 offset:1024
	ds_read_b128 v[216:219], v183 offset:2048
	ds_read_b128 v[220:223], v183 offset:3072
	global_load_lds_dwordx4 v[224:225], off
	v_lshl_add_u64 v[226:227], s[34:35], 0, v[128:129]
	s_add_i32 m0, s0, 0x2000
	s_nop 0
	global_load_lds_dwordx4 v[226:227], off
	s_setprio 1
	s_barrier
	s_waitcnt lgkmcnt(0)
	v_mfma_f32_16x16x32_bf16 v[116:119], v[208:211], v[164:167], 0
	v_mfma_f32_16x16x32_bf16 v[112:115], v[216:219], v[164:167], 0
	v_mfma_f32_16x16x32_bf16 v[100:103], v[208:211], v[184:187], 0
	v_mfma_f32_16x16x32_bf16 v[96:99], v[216:219], v[184:187], 0
	v_mfma_f32_16x16x32_bf16 v[84:87], v[208:211], v[192:195], 0
	v_mfma_f32_16x16x32_bf16 v[80:83], v[216:219], v[192:195], 0
	s_mov_b32 m0, s39
	v_mfma_f32_16x16x32_bf16 v[68:71], v[208:211], v[200:203], 0
	v_lshl_add_u64 v[228:229], s[42:43], 0, v[132:133]
	v_mfma_f32_16x16x32_bf16 v[64:67], v[216:219], v[200:203], 0
	v_mfma_f32_16x16x32_bf16 v[116:119], v[212:215], v[168:171], v[116:119]
	v_mfma_f32_16x16x32_bf16 v[112:115], v[220:223], v[168:171], v[112:115]
	v_mfma_f32_16x16x32_bf16 v[100:103], v[212:215], v[188:191], v[100:103]
	v_mfma_f32_16x16x32_bf16 v[96:99], v[220:223], v[188:191], v[96:99]
	v_mfma_f32_16x16x32_bf16 v[84:87], v[212:215], v[196:199], v[84:87]
	v_mfma_f32_16x16x32_bf16 v[80:83], v[220:223], v[196:199], v[80:83]
	v_mfma_f32_16x16x32_bf16 v[68:71], v[212:215], v[204:207], v[68:71]
	v_mfma_f32_16x16x32_bf16 v[64:67], v[220:223], v[204:207], v[64:67]
	s_barrier
	s_setprio 0
	ds_read_b128 v[164:167], v145 offset:16384
	ds_read_b128 v[168:171], v145 offset:17408
	ds_read_b128 v[184:187], v145 offset:18432
	ds_read_b128 v[188:191], v145 offset:19456
	ds_read_b128 v[192:195], v145 offset:20480
	ds_read_b128 v[196:199], v145 offset:21504
	ds_read_b128 v[200:203], v145 offset:22528
	ds_read_b128 v[204:207], v145 offset:23552
	global_load_lds_dwordx4 v[228:229], off
	v_lshl_add_u64 v[230:231], s[42:43], 0, v[130:131]
	s_mov_b32 m0, s47
	s_nop 0
	global_load_lds_dwordx4 v[230:231], off
	s_setprio 1
	s_barrier
	s_waitcnt lgkmcnt(0)
	v_mfma_f32_16x16x32_bf16 v[60:63], v[138:141], v[164:167], 0
	v_mfma_f32_16x16x32_bf16 v[56:59], v[150:153], v[164:167], 0
	v_mfma_f32_16x16x32_bf16 v[44:47], v[138:141], v[184:187], 0
	v_mfma_f32_16x16x32_bf16 v[40:43], v[150:153], v[184:187], 0
	v_mfma_f32_16x16x32_bf16 v[28:31], v[138:141], v[192:195], 0
	v_mfma_f32_16x16x32_bf16 v[24:27], v[150:153], v[192:195], 0
	v_mfma_f32_16x16x32_bf16 v[12:15], v[138:141], v[200:203], 0
	v_mfma_f32_16x16x32_bf16 v[8:11], v[150:153], v[200:203], 0
	v_mfma_f32_16x16x32_bf16 v[60:63], v[146:149], v[168:171], v[60:63]
	v_mfma_f32_16x16x32_bf16 v[56:59], v[160:163], v[168:171], v[56:59]
	v_mfma_f32_16x16x32_bf16 v[44:47], v[146:149], v[188:191], v[44:47]
	v_mfma_f32_16x16x32_bf16 v[40:43], v[160:163], v[188:191], v[40:43]
	v_mfma_f32_16x16x32_bf16 v[28:31], v[146:149], v[196:199], v[28:31]
	v_mfma_f32_16x16x32_bf16 v[24:27], v[160:163], v[196:199], v[24:27]
	v_mfma_f32_16x16x32_bf16 v[12:15], v[146:149], v[204:207], v[12:15]
	v_mfma_f32_16x16x32_bf16 v[8:11], v[160:163], v[204:207], v[8:11]
	s_barrier
; #define PG8_STAGE(bufoff, gbase, voff) do { _Pragma("unroll") for (int _i = 0; _i < 2; ++_i) \
;         __builtin_amdgcn_global_load_lds((const unsigned*)((const char*)(gbase) + (voff)[_i]), (LAS unsigned*)(lds + (bufoff) + ldsw + _i * 8192), 16, 0, 0); } while (0)
; #define PG8_LDA(dst, b, h) do { _Pragma("unroll") for (int m = 0; m < 4; ++m) _Pragma("unroll") for (int k = 0; k < 2; ++k) dst[m][k] = *(const LAS bf16x8*)(lds + PG8_SA(b, h) + aoff + m * 2048 + k * 1024); } while (0)
; #define PG8_LDB(dst, b, h) do { _Pragma("unroll") for (int n = 0; n < 2; ++n) _Pragma("unroll") for (int k = 0; k < 2; ++k) dst[n][k] = *(const LAS bf16x8*)(lds + PG8_SB(b, h) + boff + n * 2048 + k * 1024); } while (0)
; #define PG8_MMA(ai, bj, At, Bt) do { __builtin_amdgcn_s_setprio(1); _Pragma("unroll") for (int m = 0; m < 4; ++m) _Pragma("unroll") for (int n = 0; n < 2; ++n) _Pragma("unroll") for (int k = 0; k < 2; ++k) \
;         acc[ai][bj][m][n] = __builtin_amdgcn_mfma_f32_16x16x32_bf16(Bt[n][k], At[m][k], acc[ai][bj][m][n], 0, 0, 0); __builtin_amdgcn_s_setprio(0); } while (0)
; #define PG8_WAIT_V(n) asm volatile("s_waitcnt vmcnt(" #n ")" ::: "memory")
; #define PG8_WAIT_L(n) asm volatile("s_waitcnt lgkmcnt(" #n ")" ::: "memory")
; #define PG8_BAR __builtin_amdgcn_s_barrier()
; #define PG8_SCHED __builtin_amdgcn_sched_barrier(0)
; template <class Epi, class Sched>
; __device__ __forceinline__ void gemm_phase(LAS unsigned char* lds, const Gemm g, const Sched& S, const Epi& E, int tid) {
;     ...
;             PG8_STAGE(PG8_SB(0, 1), b2 + hstep, voffB);
;             PG8_WAIT_V(6); PG8_BAR; PG8_MMA(1, 1, At, B1); PG8_BAR;
;             PG8_LDB(B0, 1, 0); PG8_SCHED; PG8_LDA(At, 1, 0); PG8_STAGE(PG8_SA(0, 1), a2 + hstep, voffA);
;             PG8_WAIT_L(8); PG8_BAR; PG8_WAIT_L(0); PG8_MMA(0, 0, At, B0); PG8_BAR; PG8_SCHED;
;             PG8_LDB(B1, 1, 1); PG8_STAGE(PG8_SB(1, 0), b3, voffB);
;             PG8_BAR; PG8_WAIT_L(0); PG8_MMA(0, 1, At, B1); PG8_BAR;
;             PG8_LDA(At, 1, 1); PG8_STAGE(PG8_SA(1, 0), a3, voffA);
;             PG8_BAR; PG8_WAIT_L(0); PG8_MMA(1, 0, At, B0); PG8_BAR; PG8_SCHED;
	s_setprio 0
	s_add_u32 s0, s34, 0x40000
	s_addc_u32 s1, s35, 0
	s_add_i32 s17, s63, s45
	v_lshl_add_u64 v[138:139], s[0:1], 0, v[154:155]
	s_mov_b32 m0, s17
	s_nop 0
	global_load_lds_dwordx4 v[138:139], off
	v_lshl_add_u64 v[138:139], s[0:1], 0, v[128:129]
	s_add_i32 m0, s17, 0x2000
	s_nop 0
	global_load_lds_dwordx4 v[138:139], off
	s_waitcnt vmcnt(16)
	s_setprio 1
	s_barrier
	v_mfma_f32_16x16x32_bf16 v[52:55], v[208:211], v[164:167], 0
	v_mfma_f32_16x16x32_bf16 v[48:51], v[216:219], v[164:167], 0
	v_mfma_f32_16x16x32_bf16 v[36:39], v[208:211], v[184:187], 0
	v_mfma_f32_16x16x32_bf16 v[32:35], v[216:219], v[184:187], 0
	v_mfma_f32_16x16x32_bf16 v[20:23], v[208:211], v[192:195], 0
	v_mfma_f32_16x16x32_bf16 v[16:19], v[216:219], v[192:195], 0
	s_add_i32 s17, 0, 0x18000
	v_mfma_f32_16x16x32_bf16 v[4:7], v[208:211], v[200:203], 0
	v_add_u32_e32 v160, s17, v143
	v_mfma_f32_16x16x32_bf16 v[0:3], v[216:219], v[200:203], 0
	v_mfma_f32_16x16x32_bf16 v[52:55], v[212:215], v[168:171], v[52:55]
	v_mfma_f32_16x16x32_bf16 v[48:51], v[220:223], v[168:171], v[48:51]
	v_mfma_f32_16x16x32_bf16 v[36:39], v[212:215], v[188:191], v[36:39]
	v_mfma_f32_16x16x32_bf16 v[32:35], v[220:223], v[188:191], v[32:35]
	v_mfma_f32_16x16x32_bf16 v[20:23], v[212:215], v[196:199], v[20:23]
	v_mfma_f32_16x16x32_bf16 v[16:19], v[220:223], v[196:199], v[16:19]
	v_mfma_f32_16x16x32_bf16 v[4:7], v[212:215], v[204:207], v[4:7]
	v_mfma_f32_16x16x32_bf16 v[0:3], v[220:223], v[204:207], v[0:3]
	s_barrier
	s_setprio 0
	ds_read_b128 v[138:141], v160
	ds_read_b128 v[146:149], v160 offset:1024
	ds_read_b128 v[150:153], v160 offset:2048
	ds_read_b128 v[160:163], v160 offset:3072
	s_add_u32 s0, s42, 0x40000
	s_addc_u32 s1, s43, 0
	s_mov_b32 m0, s48
	v_lshl_add_u64 v[208:209], s[0:1], 0, v[132:133]
	ds_read_b128 v[164:167], v145 offset:32768
	ds_read_b128 v[184:187], v145 offset:34816
	ds_read_b128 v[192:195], v145 offset:36864
	ds_read_b128 v[200:203], v145 offset:38912
	global_load_lds_dwordx4 v[208:209], off
	v_lshl_add_u64 v[208:209], s[0:1], 0, v[130:131]
	s_mov_b32 m0, s49
	s_nop 0
	global_load_lds_dwordx4 v[208:209], off
	s_waitcnt lgkmcnt(4)
	s_setprio 1
	s_barrier
	s_waitcnt lgkmcnt(0)
	v_mfma_f32_16x16x32_bf16 v[124:127], v[138:141], v[164:167], v[124:127]
	ds_read_b128 v[168:171], v145 offset:33792
	v_mfma_f32_16x16x32_bf16 v[120:123], v[150:153], v[164:167], v[120:123]
	ds_read_b128 v[188:191], v145 offset:35840
	v_mfma_f32_16x16x32_bf16 v[108:111], v[138:141], v[184:187], v[108:111]
	ds_read_b128 v[196:199], v145 offset:37888
	v_mfma_f32_16x16x32_bf16 v[104:107], v[150:153], v[184:187], v[104:107]
	ds_read_b128 v[204:207], v145 offset:39936
	v_mfma_f32_16x16x32_bf16 v[92:95], v[138:141], v[192:195], v[92:95]
	v_mfma_f32_16x16x32_bf16 v[88:91], v[150:153], v[192:195], v[88:91]
	v_mfma_f32_16x16x32_bf16 v[76:79], v[138:141], v[200:203], v[76:79]
	v_mfma_f32_16x16x32_bf16 v[72:75], v[150:153], v[200:203], v[72:75]
	s_waitcnt lgkmcnt(0)
	v_mfma_f32_16x16x32_bf16 v[124:127], v[146:149], v[168:171], v[124:127]
	v_mfma_f32_16x16x32_bf16 v[120:123], v[160:163], v[168:171], v[120:123]
	v_mfma_f32_16x16x32_bf16 v[108:111], v[146:149], v[188:191], v[108:111]
	v_mfma_f32_16x16x32_bf16 v[104:107], v[160:163], v[188:191], v[104:107]
	v_mfma_f32_16x16x32_bf16 v[92:95], v[146:149], v[196:199], v[92:95]
	v_mfma_f32_16x16x32_bf16 v[88:91], v[160:163], v[196:199], v[88:91]
	v_mfma_f32_16x16x32_bf16 v[76:79], v[146:149], v[204:207], v[76:79]
	v_mfma_f32_16x16x32_bf16 v[72:75], v[160:163], v[204:207], v[72:75]
	s_barrier
	s_setprio 0
	s_add_i32 s42, 0, 0x1c000
	s_add_i32 s0, s17, s45
	v_add_u32_e32 v183, s42, v143
	v_lshl_add_u64 v[224:225], v[224:225], 0, s[8:9]
	s_mov_b32 m0, s0
	ds_read_b128 v[208:211], v183
	ds_read_b128 v[212:215], v183 offset:1024
	ds_read_b128 v[216:219], v183 offset:2048
	ds_read_b128 v[220:223], v183 offset:3072
	global_load_lds_dwordx4 v[224:225], off
	v_lshl_add_u64 v[224:225], v[226:227], 0, s[8:9]
	s_add_i32 m0, s0, 0x2000
	s_nop 0
	global_load_lds_dwordx4 v[224:225], off
	s_waitcnt vmcnt(10)
	s_setprio 1
	s_barrier
	s_waitcnt lgkmcnt(0)
	v_mfma_f32_16x16x32_bf16 v[116:119], v[208:211], v[164:167], v[116:119]
	v_mfma_f32_16x16x32_bf16 v[112:115], v[216:219], v[164:167], v[112:115]
	v_mfma_f32_16x16x32_bf16 v[100:103], v[208:211], v[184:187], v[100:103]
	v_mfma_f32_16x16x32_bf16 v[96:99], v[216:219], v[184:187], v[96:99]
	v_mfma_f32_16x16x32_bf16 v[84:87], v[208:211], v[192:195], v[84:87]
	v_mfma_f32_16x16x32_bf16 v[80:83], v[216:219], v[192:195], v[80:83]
	s_mov_b32 m0, s6
	v_mfma_f32_16x16x32_bf16 v[68:71], v[208:211], v[200:203], v[68:71]
	v_lshl_add_u64 v[224:225], v[228:229], 0, s[8:9]
	v_mfma_f32_16x16x32_bf16 v[64:67], v[216:219], v[200:203], v[64:67]
	v_mfma_f32_16x16x32_bf16 v[116:119], v[212:215], v[168:171], v[116:119]
	v_mfma_f32_16x16x32_bf16 v[112:115], v[220:223], v[168:171], v[112:115]
	v_mfma_f32_16x16x32_bf16 v[100:103], v[212:215], v[188:191], v[100:103]
	v_mfma_f32_16x16x32_bf16 v[96:99], v[220:223], v[188:191], v[96:99]
	v_mfma_f32_16x16x32_bf16 v[84:87], v[212:215], v[196:199], v[84:87]
	v_mfma_f32_16x16x32_bf16 v[80:83], v[220:223], v[196:199], v[80:83]
	v_mfma_f32_16x16x32_bf16 v[68:71], v[212:215], v[204:207], v[68:71]
	v_mfma_f32_16x16x32_bf16 v[64:67], v[220:223], v[204:207], v[64:67]
	s_barrier
	s_setprio 0
	ds_read_b128 v[164:167], v145 offset:49152
	ds_read_b128 v[168:171], v145 offset:50176
	ds_read_b128 v[184:187], v145 offset:51200
	ds_read_b128 v[188:191], v145 offset:52224
	ds_read_b128 v[192:195], v145 offset:53248
	ds_read_b128 v[196:199], v145 offset:54272
	ds_read_b128 v[200:203], v145 offset:55296
	ds_read_b128 v[204:207], v145 offset:56320
	global_load_lds_dwordx4 v[224:225], off
	v_lshl_add_u64 v[224:225], v[230:231], 0, s[8:9]
	s_mov_b32 m0, s50
	s_nop 0
	global_load_lds_dwordx4 v[224:225], off
	s_setprio 1
	s_barrier
; #define PG8_STAGE(bufoff, gbase, voff) do { _Pragma("unroll") for (int _i = 0; _i < 2; ++_i) \
;         __builtin_amdgcn_global_load_lds((const unsigned*)((const char*)(gbase) + (voff)[_i]), (LAS unsigned*)(lds + (bufoff) + ldsw + _i * 8192), 16, 0, 0); } while (0)
; #define PG8_LDA(dst, b, h) do { _Pragma("unroll") for (int m = 0; m < 4; ++m) _Pragma("unroll") for (int k = 0; k < 2; ++k) dst[m][k] = *(const LAS bf16x8*)(lds + PG8_SA(b, h) + aoff + m * 2048 + k * 1024); } while (0)
; #define PG8_LDB(dst, b, h) do { _Pragma("unroll") for (int n = 0; n < 2; ++n) _Pragma("unroll") for (int k = 0; k < 2; ++k) dst[n][k] = *(const LAS bf16x8*)(lds + PG8_SB(b, h) + boff + n * 2048 + k * 1024); } while (0)
; #define PG8_MMA(ai, bj, At, Bt) do { __builtin_amdgcn_s_setprio(1); _Pragma("unroll") for (int m = 0; m < 4; ++m) _Pragma("unroll") for (int n = 0; n < 2; ++n) _Pragma("unroll") for (int k = 0; k < 2; ++k) \
;         acc[ai][bj][m][n] = __builtin_amdgcn_mfma_f32_16x16x32_bf16(Bt[n][k], At[m][k], acc[ai][bj][m][n], 0, 0, 0); __builtin_amdgcn_s_setprio(0); } while (0)
; #define PG8_WAIT_V(n) asm volatile("s_waitcnt vmcnt(" #n ")" ::: "memory")
; #define PG8_WAIT_L(n) asm volatile("s_waitcnt lgkmcnt(" #n ")" ::: "memory")
; #define PG8_BAR __builtin_amdgcn_s_barrier()
; template <class Epi, class Sched>
; __device__ __forceinline__ void gemm_phase(LAS unsigned char* lds, const Gemm g, const Sched& S, const Epi& E, int tid) {
;     ...
;         for (int t = 0; t < nt; t += 2) {
;             const bool last = (t == nt - 2);
;             const char* a1 = cA + (size_t)(t + 1) * kstep;
;             const char* a2 = last ? nA : cA + (size_t)(t + 2) * kstep; const char* b2 = last ? nB : cB + (size_t)(t + 2) * kstep;
;             const char* a3 = a2 + kstep; const char* b3 = b2 + kstep;
;             PG8_LDB(B0, 0, 0); PG8_SCHED; PG8_LDA(At, 0, 0); PG8_STAGE(PG8_SA(1, 1), a1 + hstep, voffA);
;             PG8_WAIT_L(8); PG8_BAR; PG8_WAIT_L(0); PG8_MMA(0, 0, At, B0); PG8_BAR; PG8_SCHED;
;             PG8_LDB(B1, 0, 1); PG8_STAGE(PG8_SB(0, 0), b2, voffB);
;             PG8_BAR; PG8_WAIT_L(0); PG8_MMA(0, 1, At, B1); PG8_BAR;
;     ...
;             PG8_BAR; PG8_WAIT_L(0); PG8_MMA(1, 0, At, B0); PG8_BAR; PG8_SCHED;
;             PG8_STAGE(PG8_SB(1, 1), b3 + hstep, voffB);
;             PG8_WAIT_V(6); PG8_BAR; PG8_MMA(1, 1, At, B1); PG8_BAR;
	s_waitcnt lgkmcnt(0)
	v_mfma_f32_16x16x32_bf16 v[60:63], v[138:141], v[164:167], v[60:63]
	v_mfma_f32_16x16x32_bf16 v[56:59], v[150:153], v[164:167], v[56:59]
	v_mfma_f32_16x16x32_bf16 v[44:47], v[138:141], v[184:187], v[44:47]
	v_mfma_f32_16x16x32_bf16 v[40:43], v[150:153], v[184:187], v[40:43]
	v_mfma_f32_16x16x32_bf16 v[28:31], v[138:141], v[192:195], v[28:31]
	v_mfma_f32_16x16x32_bf16 v[24:27], v[150:153], v[192:195], v[24:27]
	v_mfma_f32_16x16x32_bf16 v[12:15], v[138:141], v[200:203], v[12:15]
	v_mfma_f32_16x16x32_bf16 v[8:11], v[150:153], v[200:203], v[8:11]
	v_mfma_f32_16x16x32_bf16 v[60:63], v[146:149], v[168:171], v[60:63]
	v_mfma_f32_16x16x32_bf16 v[56:59], v[160:163], v[168:171], v[56:59]
	v_mfma_f32_16x16x32_bf16 v[44:47], v[146:149], v[188:191], v[44:47]
	v_mfma_f32_16x16x32_bf16 v[40:43], v[160:163], v[188:191], v[40:43]
	v_mfma_f32_16x16x32_bf16 v[28:31], v[146:149], v[196:199], v[28:31]
	v_mfma_f32_16x16x32_bf16 v[24:27], v[160:163], v[196:199], v[24:27]
	v_mfma_f32_16x16x32_bf16 v[12:15], v[146:149], v[204:207], v[12:15]
	v_mfma_f32_16x16x32_bf16 v[8:11], v[160:163], v[204:207], v[8:11]
	s_barrier
	s_setprio 0
	s_add_u32 s0, s34, 0x40080
	s_addc_u32 s1, s35, 0
	s_add_i32 s17, s42, s45
	v_lshl_add_u64 v[138:139], s[0:1], 0, v[154:155]
	s_mov_b32 m0, s17
	s_nop 0
	global_load_lds_dwordx4 v[138:139], off
	v_lshl_add_u64 v[138:139], s[0:1], 0, v[128:129]
	s_add_i32 m0, s17, 0x2000
	s_nop 0
	global_load_lds_dwordx4 v[138:139], off
	s_waitcnt vmcnt(6)
	s_setprio 1
	s_barrier
	v_mfma_f32_16x16x32_bf16 v[52:55], v[208:211], v[164:167], v[52:55]
	v_mfma_f32_16x16x32_bf16 v[48:51], v[216:219], v[164:167], v[48:51]
	v_mfma_f32_16x16x32_bf16 v[36:39], v[208:211], v[184:187], v[36:39]
	v_mfma_f32_16x16x32_bf16 v[32:35], v[216:219], v[184:187], v[32:35]
	v_mfma_f32_16x16x32_bf16 v[20:23], v[208:211], v[192:195], v[20:23]
	v_mfma_f32_16x16x32_bf16 v[16:19], v[216:219], v[192:195], v[16:19]
	s_add_i32 s61, s61, 2
	v_mfma_f32_16x16x32_bf16 v[4:7], v[208:211], v[200:203], v[4:7]
	s_add_u32 s40, s40, 0x100
	v_mfma_f32_16x16x32_bf16 v[0:3], v[216:219], v[200:203], v[0:3]
	s_addc_u32 s41, s41, 0
	v_mfma_f32_16x16x32_bf16 v[52:55], v[212:215], v[168:171], v[52:55]
	s_add_u32 s58, s58, 0x100
	v_mfma_f32_16x16x32_bf16 v[48:51], v[220:223], v[168:171], v[48:51]
	s_addc_u32 s60, s60, 0
	v_mfma_f32_16x16x32_bf16 v[36:39], v[212:215], v[188:191], v[36:39]
	s_cmp_gt_u32 s61, 13
	v_mfma_f32_16x16x32_bf16 v[32:35], v[220:223], v[188:191], v[32:35]
	v_mfma_f32_16x16x32_bf16 v[20:23], v[212:215], v[196:199], v[20:23]
	v_mfma_f32_16x16x32_bf16 v[16:19], v[220:223], v[196:199], v[16:19]
	v_mfma_f32_16x16x32_bf16 v[4:7], v[212:215], v[204:207], v[4:7]
	v_mfma_f32_16x16x32_bf16 v[0:3], v[220:223], v[204:207], v[0:3]
	s_cbranch_scc1 .Lx_nobar_swiglu
	s_barrier
	s_setprio 0
.LBB0_115:
	s_add_u32 s0, s40, 0xfffc0080
	s_addc_u32 s1, s41, -1
	s_add_i32 s17, 0, 0x10000
	v_add_u32_e32 v160, s17, v143
	ds_read_b128 v[138:141], v160
	ds_read_b128 v[146:149], v160 offset:1024
	ds_read_b128 v[150:153], v160 offset:2048
	ds_read_b128 v[160:163], v160 offset:3072
	s_cmp_eq_u32 s61, 12
	s_cselect_b32 s43, s25, s1
	s_cselect_b32 s42, s53, s0
	s_cselect_b32 s35, s15, s60
	s_cselect_b32 s34, s55, s58
	v_lshl_add_u64 v[208:209], s[40:41], 0, v[134:135]
	s_add_i32 m0, s39, 0xc000
	ds_read_b128 v[164:167], v145
	ds_read_b128 v[184:187], v145 offset:2048
	ds_read_b128 v[192:195], v145 offset:4096
	ds_read_b128 v[200:203], v145 offset:6144
	global_load_lds_dwordx4 v[208:209], off
	v_lshl_add_u64 v[208:209], s[40:41], 0, v[136:137]
	s_add_i32 m0, s39, 0xe000
	s_nop 0
	global_load_lds_dwordx4 v[208:209], off
	s_waitcnt lgkmcnt(4)
	s_setprio 1
	s_barrier
	s_waitcnt lgkmcnt(0)
	v_mfma_f32_16x16x32_bf16 v[124:127], v[138:141], v[164:167], v[124:127]
	ds_read_b128 v[168:171], v145 offset:1024
	v_mfma_f32_16x16x32_bf16 v[120:123], v[150:153], v[164:167], v[120:123]
	ds_read_b128 v[188:191], v145 offset:3072
	v_mfma_f32_16x16x32_bf16 v[108:111], v[138:141], v[184:187], v[108:111]
	ds_read_b128 v[196:199], v145 offset:5120
	v_mfma_f32_16x16x32_bf16 v[104:107], v[150:153], v[184:187], v[104:107]
	ds_read_b128 v[204:207], v145 offset:7168
	v_mfma_f32_16x16x32_bf16 v[92:95], v[138:141], v[192:195], v[92:95]
	v_mfma_f32_16x16x32_bf16 v[88:91], v[150:153], v[192:195], v[88:91]
	v_mfma_f32_16x16x32_bf16 v[76:79], v[138:141], v[200:203], v[76:79]
	v_mfma_f32_16x16x32_bf16 v[72:75], v[150:153], v[200:203], v[72:75]
	s_waitcnt lgkmcnt(0)
	v_mfma_f32_16x16x32_bf16 v[124:127], v[146:149], v[168:171], v[124:127]
	v_mfma_f32_16x16x32_bf16 v[120:123], v[160:163], v[168:171], v[120:123]
	v_mfma_f32_16x16x32_bf16 v[108:111], v[146:149], v[188:191], v[108:111]
	v_mfma_f32_16x16x32_bf16 v[104:107], v[160:163], v[188:191], v[104:107]
	v_mfma_f32_16x16x32_bf16 v[92:95], v[146:149], v[196:199], v[92:95]
	v_mfma_f32_16x16x32_bf16 v[88:91], v[160:163], v[196:199], v[88:91]
	v_mfma_f32_16x16x32_bf16 v[76:79], v[146:149], v[204:207], v[76:79]
	v_mfma_f32_16x16x32_bf16 v[72:75], v[160:163], v[204:207], v[72:75]
	s_barrier
	s_setprio 0
	s_add_i32 s63, 0, 0x14000
	s_add_i32 s0, s17, s45
	v_add_u32_e32 v183, s63, v143
	v_lshl_add_u64 v[224:225], s[34:35], 0, v[154:155]
	s_mov_b32 m0, s0
	ds_read_b128 v[208:211], v183
	ds_read_b128 v[212:215], v183 offset:1024
	ds_read_b128 v[216:219], v183 offset:2048
	ds_read_b128 v[220:223], v183 offset:3072
	global_load_lds_dwordx4 v[224:225], off
	v_lshl_add_u64 v[226:227], s[34:35], 0, v[128:129]
	s_add_i32 m0, s0, 0x2000
	s_nop 0
	global_load_lds_dwordx4 v[226:227], off
	s_setprio 1
	s_barrier
; #define PG8_STAGE(bufoff, gbase, voff) do { _Pragma("unroll") for (int _i = 0; _i < 2; ++_i) \
;         __builtin_amdgcn_global_load_lds((const unsigned*)((const char*)(gbase) + (voff)[_i]), (LAS unsigned*)(lds + (bufoff) + ldsw + _i * 8192), 16, 0, 0); } while (0)
; #define PG8_LDA(dst, b, h) do { _Pragma("unroll") for (int m = 0; m < 4; ++m) _Pragma("unroll") for (int k = 0; k < 2; ++k) dst[m][k] = *(const LAS bf16x8*)(lds + PG8_SA(b, h) + aoff + m * 2048 + k * 1024); } while (0)
; #define PG8_LDB(dst, b, h) do { _Pragma("unroll") for (int n = 0; n < 2; ++n) _Pragma("unroll") for (int k = 0; k < 2; ++k) dst[n][k] = *(const LAS bf16x8*)(lds + PG8_SB(b, h) + boff + n * 2048 + k * 1024); } while (0)
; #define PG8_MMA(ai, bj, At, Bt) do { __builtin_amdgcn_s_setprio(1); _Pragma("unroll") for (int m = 0; m < 4; ++m) _Pragma("unroll") for (int n = 0; n < 2; ++n) _Pragma("unroll") for (int k = 0; k < 2; ++k) \
;         acc[ai][bj][m][n] = __builtin_amdgcn_mfma_f32_16x16x32_bf16(Bt[n][k], At[m][k], acc[ai][bj][m][n], 0, 0, 0); __builtin_amdgcn_s_setprio(0); } while (0)
; #define PG8_WAIT_V(n) asm volatile("s_waitcnt vmcnt(" #n ")" ::: "memory")
; #define PG8_WAIT_L(n) asm volatile("s_waitcnt lgkmcnt(" #n ")" ::: "memory")
; #define PG8_BAR __builtin_amdgcn_s_barrier()
; #define PG8_SCHED __builtin_amdgcn_sched_barrier(0)
; template <class Epi, class Sched>
; __device__ __forceinline__ void gemm_phase(LAS unsigned char* lds, const Gemm g, const Sched& S, const Epi& E, int tid) {
;     ...
;             PG8_LDB(B1, 0, 1); PG8_STAGE(PG8_SB(0, 0), b2, voffB);
;             PG8_BAR; PG8_WAIT_L(0); PG8_MMA(0, 1, At, B1); PG8_BAR;
;             PG8_LDA(At, 0, 1); PG8_STAGE(PG8_SA(0, 0), a2, voffA);
;             PG8_BAR; PG8_WAIT_L(0); PG8_MMA(1, 0, At, B0); PG8_BAR; PG8_SCHED;
;             PG8_STAGE(PG8_SB(0, 1), b2 + hstep, voffB);
;             PG8_WAIT_V(6); PG8_BAR; PG8_MMA(1, 1, At, B1); PG8_BAR;
;             PG8_LDB(B0, 1, 0); PG8_SCHED; PG8_LDA(At, 1, 0); PG8_STAGE(PG8_SA(0, 1), a2 + hstep, voffA);
	s_waitcnt lgkmcnt(0)
	v_mfma_f32_16x16x32_bf16 v[116:119], v[208:211], v[164:167], v[116:119]
	v_mfma_f32_16x16x32_bf16 v[112:115], v[216:219], v[164:167], v[112:115]
	v_mfma_f32_16x16x32_bf16 v[100:103], v[208:211], v[184:187], v[100:103]
	v_mfma_f32_16x16x32_bf16 v[96:99], v[216:219], v[184:187], v[96:99]
	v_mfma_f32_16x16x32_bf16 v[84:87], v[208:211], v[192:195], v[84:87]
	v_mfma_f32_16x16x32_bf16 v[80:83], v[216:219], v[192:195], v[80:83]
	s_mov_b32 m0, s39
	v_mfma_f32_16x16x32_bf16 v[68:71], v[208:211], v[200:203], v[68:71]
	v_lshl_add_u64 v[228:229], s[42:43], 0, v[132:133]
	v_mfma_f32_16x16x32_bf16 v[64:67], v[216:219], v[200:203], v[64:67]
	v_mfma_f32_16x16x32_bf16 v[116:119], v[212:215], v[168:171], v[116:119]
	v_mfma_f32_16x16x32_bf16 v[112:115], v[220:223], v[168:171], v[112:115]
	v_mfma_f32_16x16x32_bf16 v[100:103], v[212:215], v[188:191], v[100:103]
	v_mfma_f32_16x16x32_bf16 v[96:99], v[220:223], v[188:191], v[96:99]
	v_mfma_f32_16x16x32_bf16 v[84:87], v[212:215], v[196:199], v[84:87]
	v_mfma_f32_16x16x32_bf16 v[80:83], v[220:223], v[196:199], v[80:83]
	v_mfma_f32_16x16x32_bf16 v[68:71], v[212:215], v[204:207], v[68:71]
	v_mfma_f32_16x16x32_bf16 v[64:67], v[220:223], v[204:207], v[64:67]
	s_barrier
	s_setprio 0
	ds_read_b128 v[164:167], v145 offset:16384
	ds_read_b128 v[168:171], v145 offset:17408
	ds_read_b128 v[184:187], v145 offset:18432
	ds_read_b128 v[188:191], v145 offset:19456
	ds_read_b128 v[192:195], v145 offset:20480
	ds_read_b128 v[196:199], v145 offset:21504
	ds_read_b128 v[200:203], v145 offset:22528
	ds_read_b128 v[204:207], v145 offset:23552
	global_load_lds_dwordx4 v[228:229], off
	v_lshl_add_u64 v[230:231], s[42:43], 0, v[130:131]
	s_mov_b32 m0, s47
	s_nop 0
	global_load_lds_dwordx4 v[230:231], off
	s_setprio 1
	s_barrier
	s_waitcnt lgkmcnt(0)
	v_mfma_f32_16x16x32_bf16 v[60:63], v[138:141], v[164:167], v[60:63]
	v_mfma_f32_16x16x32_bf16 v[56:59], v[150:153], v[164:167], v[56:59]
	v_mfma_f32_16x16x32_bf16 v[44:47], v[138:141], v[184:187], v[44:47]
	v_mfma_f32_16x16x32_bf16 v[40:43], v[150:153], v[184:187], v[40:43]
	v_mfma_f32_16x16x32_bf16 v[28:31], v[138:141], v[192:195], v[28:31]
	v_mfma_f32_16x16x32_bf16 v[24:27], v[150:153], v[192:195], v[24:27]
	v_mfma_f32_16x16x32_bf16 v[12:15], v[138:141], v[200:203], v[12:15]
	v_mfma_f32_16x16x32_bf16 v[8:11], v[150:153], v[200:203], v[8:11]
	v_mfma_f32_16x16x32_bf16 v[60:63], v[146:149], v[168:171], v[60:63]
	v_mfma_f32_16x16x32_bf16 v[56:59], v[160:163], v[168:171], v[56:59]
	v_mfma_f32_16x16x32_bf16 v[44:47], v[146:149], v[188:191], v[44:47]
	v_mfma_f32_16x16x32_bf16 v[40:43], v[160:163], v[188:191], v[40:43]
	v_mfma_f32_16x16x32_bf16 v[28:31], v[146:149], v[196:199], v[28:31]
	v_mfma_f32_16x16x32_bf16 v[24:27], v[160:163], v[196:199], v[24:27]
	v_mfma_f32_16x16x32_bf16 v[12:15], v[146:149], v[204:207], v[12:15]
	v_mfma_f32_16x16x32_bf16 v[8:11], v[160:163], v[204:207], v[8:11]
	s_barrier
	s_setprio 0
	s_add_u32 s0, s34, 0x40000
	s_addc_u32 s1, s35, 0
	s_add_i32 s17, s63, s45
	v_lshl_add_u64 v[138:139], s[0:1], 0, v[154:155]
	s_mov_b32 m0, s17
	s_nop 0
	global_load_lds_dwordx4 v[138:139], off
	v_lshl_add_u64 v[138:139], s[0:1], 0, v[128:129]
	s_add_i32 m0, s17, 0x2000
	s_nop 0
	global_load_lds_dwordx4 v[138:139], off
	s_waitcnt vmcnt(6)
	s_setprio 1
	s_barrier
	v_mfma_f32_16x16x32_bf16 v[52:55], v[208:211], v[164:167], v[52:55]
	v_mfma_f32_16x16x32_bf16 v[48:51], v[216:219], v[164:167], v[48:51]
	v_mfma_f32_16x16x32_bf16 v[36:39], v[208:211], v[184:187], v[36:39]
	v_mfma_f32_16x16x32_bf16 v[32:35], v[216:219], v[184:187], v[32:35]
	v_mfma_f32_16x16x32_bf16 v[20:23], v[208:211], v[192:195], v[20:23]
	v_mfma_f32_16x16x32_bf16 v[16:19], v[216:219], v[192:195], v[16:19]
	s_add_i32 s17, 0, 0x18000
	v_mfma_f32_16x16x32_bf16 v[4:7], v[208:211], v[200:203], v[4:7]
	v_add_u32_e32 v160, s17, v143
	v_mfma_f32_16x16x32_bf16 v[0:3], v[216:219], v[200:203], v[0:3]
	v_mfma_f32_16x16x32_bf16 v[52:55], v[212:215], v[168:171], v[52:55]
	v_mfma_f32_16x16x32_bf16 v[48:51], v[220:223], v[168:171], v[48:51]
	v_mfma_f32_16x16x32_bf16 v[36:39], v[212:215], v[188:191], v[36:39]
	v_mfma_f32_16x16x32_bf16 v[32:35], v[220:223], v[188:191], v[32:35]
	v_mfma_f32_16x16x32_bf16 v[20:23], v[212:215], v[196:199], v[20:23]
	v_mfma_f32_16x16x32_bf16 v[16:19], v[220:223], v[196:199], v[16:19]
	v_mfma_f32_16x16x32_bf16 v[4:7], v[212:215], v[204:207], v[4:7]
	v_mfma_f32_16x16x32_bf16 v[0:3], v[220:223], v[204:207], v[0:3]
	s_barrier
	s_setprio 0
	ds_read_b128 v[138:141], v160
	ds_read_b128 v[146:149], v160 offset:1024
	ds_read_b128 v[150:153], v160 offset:2048
	ds_read_b128 v[160:163], v160 offset:3072
	s_add_u32 s0, s42, 0x40000
	s_addc_u32 s1, s43, 0
	s_mov_b32 m0, s48
	v_lshl_add_u64 v[208:209], s[0:1], 0, v[132:133]
	ds_read_b128 v[164:167], v145 offset:32768
	ds_read_b128 v[184:187], v145 offset:34816
	ds_read_b128 v[192:195], v145 offset:36864
	ds_read_b128 v[200:203], v145 offset:38912
	global_load_lds_dwordx4 v[208:209], off
	v_lshl_add_u64 v[208:209], s[0:1], 0, v[130:131]
	s_mov_b32 m0, s49
	s_nop 0
	global_load_lds_dwordx4 v[208:209], off
	s_waitcnt lgkmcnt(4)
	s_setprio 1
	s_barrier
; #define PG8_STAGE(bufoff, gbase, voff) do { _Pragma("unroll") for (int _i = 0; _i < 2; ++_i) \
;         __builtin_amdgcn_global_load_lds((const unsigned*)((const char*)(gbase) + (voff)[_i]), (LAS unsigned*)(lds + (bufoff) + ldsw + _i * 8192), 16, 0, 0); } while (0)
; #define PG8_LDA(dst, b, h) do { _Pragma("unroll") for (int m = 0; m < 4; ++m) _Pragma("unroll") for (int k = 0; k < 2; ++k) dst[m][k] = *(const LAS bf16x8*)(lds + PG8_SA(b, h) + aoff + m * 2048 + k * 1024); } while (0)
; #define PG8_LDB(dst, b, h) do { _Pragma("unroll") for (int n = 0; n < 2; ++n) _Pragma("unroll") for (int k = 0; k < 2; ++k) dst[n][k] = *(const LAS bf16x8*)(lds + PG8_SB(b, h) + boff + n * 2048 + k * 1024); } while (0)
; #define PG8_MMA(ai, bj, At, Bt) do { __builtin_amdgcn_s_setprio(1); _Pragma("unroll") for (int m = 0; m < 4; ++m) _Pragma("unroll") for (int n = 0; n < 2; ++n) _Pragma("unroll") for (int k = 0; k < 2; ++k) \
;         acc[ai][bj][m][n] = __builtin_amdgcn_mfma_f32_16x16x32_bf16(Bt[n][k], At[m][k], acc[ai][bj][m][n], 0, 0, 0); __builtin_amdgcn_s_setprio(0); } while (0)
; #define PG8_WAIT_V(n) asm volatile("s_waitcnt vmcnt(" #n ")" ::: "memory")
; #define PG8_WAIT_L(n) asm volatile("s_waitcnt lgkmcnt(" #n ")" ::: "memory")
; #define PG8_BAR __builtin_amdgcn_s_barrier()
; #define PG8_SCHED __builtin_amdgcn_sched_barrier(0)
; template <class Epi, class Sched>
; __device__ __forceinline__ void gemm_phase(LAS unsigned char* lds, const Gemm g, const Sched& S, const Epi& E, int tid) {
;     ...
;             PG8_LDB(B0, 1, 0); PG8_SCHED; PG8_LDA(At, 1, 0); PG8_STAGE(PG8_SA(0, 1), a2 + hstep, voffA);
;             PG8_WAIT_L(8); PG8_BAR; PG8_WAIT_L(0); PG8_MMA(0, 0, At, B0); PG8_BAR; PG8_SCHED;
;             PG8_LDB(B1, 1, 1); PG8_STAGE(PG8_SB(1, 0), b3, voffB);
;             PG8_BAR; PG8_WAIT_L(0); PG8_MMA(0, 1, At, B1); PG8_BAR;
;             PG8_LDA(At, 1, 1); PG8_STAGE(PG8_SA(1, 0), a3, voffA);
;             PG8_BAR; PG8_WAIT_L(0); PG8_MMA(1, 0, At, B0); PG8_BAR; PG8_SCHED;
;             PG8_STAGE(PG8_SB(1, 1), b3 + hstep, voffB);
;             PG8_WAIT_V(6); PG8_BAR; PG8_MMA(1, 1, At, B1); PG8_BAR;
	s_waitcnt lgkmcnt(0)
	v_mfma_f32_16x16x32_bf16 v[124:127], v[138:141], v[164:167], v[124:127]
	ds_read_b128 v[168:171], v145 offset:33792
	v_mfma_f32_16x16x32_bf16 v[120:123], v[150:153], v[164:167], v[120:123]
	ds_read_b128 v[188:191], v145 offset:35840
	v_mfma_f32_16x16x32_bf16 v[108:111], v[138:141], v[184:187], v[108:111]
	ds_read_b128 v[196:199], v145 offset:37888
	v_mfma_f32_16x16x32_bf16 v[104:107], v[150:153], v[184:187], v[104:107]
	ds_read_b128 v[204:207], v145 offset:39936
	v_mfma_f32_16x16x32_bf16 v[92:95], v[138:141], v[192:195], v[92:95]
	v_mfma_f32_16x16x32_bf16 v[88:91], v[150:153], v[192:195], v[88:91]
	v_mfma_f32_16x16x32_bf16 v[76:79], v[138:141], v[200:203], v[76:79]
	v_mfma_f32_16x16x32_bf16 v[72:75], v[150:153], v[200:203], v[72:75]
	s_waitcnt lgkmcnt(0)
	v_mfma_f32_16x16x32_bf16 v[124:127], v[146:149], v[168:171], v[124:127]
	v_mfma_f32_16x16x32_bf16 v[120:123], v[160:163], v[168:171], v[120:123]
	v_mfma_f32_16x16x32_bf16 v[108:111], v[146:149], v[188:191], v[108:111]
	v_mfma_f32_16x16x32_bf16 v[104:107], v[160:163], v[188:191], v[104:107]
	v_mfma_f32_16x16x32_bf16 v[92:95], v[146:149], v[196:199], v[92:95]
	v_mfma_f32_16x16x32_bf16 v[88:91], v[160:163], v[196:199], v[88:91]
	v_mfma_f32_16x16x32_bf16 v[76:79], v[146:149], v[204:207], v[76:79]
	v_mfma_f32_16x16x32_bf16 v[72:75], v[160:163], v[204:207], v[72:75]
	s_barrier
	s_setprio 0
	s_add_i32 s42, 0, 0x1c000
	s_add_i32 s0, s17, s45
	v_add_u32_e32 v183, s42, v143
	v_lshl_add_u64 v[224:225], v[224:225], 0, s[8:9]
	s_mov_b32 m0, s0
	ds_read_b128 v[208:211], v183
	ds_read_b128 v[212:215], v183 offset:1024
	ds_read_b128 v[216:219], v183 offset:2048
	ds_read_b128 v[220:223], v183 offset:3072
	global_load_lds_dwordx4 v[224:225], off
	v_lshl_add_u64 v[224:225], v[226:227], 0, s[8:9]
	s_add_i32 m0, s0, 0x2000
	s_nop 0
	global_load_lds_dwordx4 v[224:225], off
	s_setprio 1
	s_barrier
	s_waitcnt lgkmcnt(0)
	v_mfma_f32_16x16x32_bf16 v[116:119], v[208:211], v[164:167], v[116:119]
	v_mfma_f32_16x16x32_bf16 v[112:115], v[216:219], v[164:167], v[112:115]
	v_mfma_f32_16x16x32_bf16 v[100:103], v[208:211], v[184:187], v[100:103]
	v_mfma_f32_16x16x32_bf16 v[96:99], v[216:219], v[184:187], v[96:99]
	v_mfma_f32_16x16x32_bf16 v[84:87], v[208:211], v[192:195], v[84:87]
	v_mfma_f32_16x16x32_bf16 v[80:83], v[216:219], v[192:195], v[80:83]
	s_mov_b32 m0, s6
	v_mfma_f32_16x16x32_bf16 v[68:71], v[208:211], v[200:203], v[68:71]
	v_lshl_add_u64 v[224:225], v[228:229], 0, s[8:9]
	v_mfma_f32_16x16x32_bf16 v[64:67], v[216:219], v[200:203], v[64:67]
	v_mfma_f32_16x16x32_bf16 v[116:119], v[212:215], v[168:171], v[116:119]
	v_mfma_f32_16x16x32_bf16 v[112:115], v[220:223], v[168:171], v[112:115]
	v_mfma_f32_16x16x32_bf16 v[100:103], v[212:215], v[188:191], v[100:103]
	v_mfma_f32_16x16x32_bf16 v[96:99], v[220:223], v[188:191], v[96:99]
	v_mfma_f32_16x16x32_bf16 v[84:87], v[212:215], v[196:199], v[84:87]
	v_mfma_f32_16x16x32_bf16 v[80:83], v[220:223], v[196:199], v[80:83]
	v_mfma_f32_16x16x32_bf16 v[68:71], v[212:215], v[204:207], v[68:71]
	v_mfma_f32_16x16x32_bf16 v[64:67], v[220:223], v[204:207], v[64:67]
	s_barrier
	s_setprio 0
	ds_read_b128 v[164:167], v145 offset:49152
	ds_read_b128 v[168:171], v145 offset:50176
	ds_read_b128 v[184:187], v145 offset:51200
	ds_read_b128 v[188:191], v145 offset:52224
	ds_read_b128 v[192:195], v145 offset:53248
	ds_read_b128 v[196:199], v145 offset:54272
	ds_read_b128 v[200:203], v145 offset:55296
	ds_read_b128 v[204:207], v145 offset:56320
	global_load_lds_dwordx4 v[224:225], off
	v_lshl_add_u64 v[224:225], v[230:231], 0, s[8:9]
	s_mov_b32 m0, s50
	s_nop 0
	global_load_lds_dwordx4 v[224:225], off
	s_setprio 1
	s_barrier
	s_waitcnt lgkmcnt(0)
	v_mfma_f32_16x16x32_bf16 v[60:63], v[138:141], v[164:167], v[60:63]
	v_mfma_f32_16x16x32_bf16 v[56:59], v[150:153], v[164:167], v[56:59]
	v_mfma_f32_16x16x32_bf16 v[44:47], v[138:141], v[184:187], v[44:47]
	v_mfma_f32_16x16x32_bf16 v[40:43], v[150:153], v[184:187], v[40:43]
	v_mfma_f32_16x16x32_bf16 v[28:31], v[138:141], v[192:195], v[28:31]
	v_mfma_f32_16x16x32_bf16 v[24:27], v[150:153], v[192:195], v[24:27]
	v_mfma_f32_16x16x32_bf16 v[12:15], v[138:141], v[200:203], v[12:15]
	v_mfma_f32_16x16x32_bf16 v[8:11], v[150:153], v[200:203], v[8:11]
	v_mfma_f32_16x16x32_bf16 v[60:63], v[146:149], v[168:171], v[60:63]
	v_mfma_f32_16x16x32_bf16 v[56:59], v[160:163], v[168:171], v[56:59]
	v_mfma_f32_16x16x32_bf16 v[44:47], v[146:149], v[188:191], v[44:47]
	v_mfma_f32_16x16x32_bf16 v[40:43], v[160:163], v[188:191], v[40:43]
	v_mfma_f32_16x16x32_bf16 v[28:31], v[146:149], v[196:199], v[28:31]
	v_mfma_f32_16x16x32_bf16 v[24:27], v[160:163], v[196:199], v[24:27]
	v_mfma_f32_16x16x32_bf16 v[12:15], v[146:149], v[204:207], v[12:15]
	v_mfma_f32_16x16x32_bf16 v[8:11], v[160:163], v[204:207], v[8:11]
	s_barrier
	s_setprio 0
	s_add_u32 s0, s34, 0x40080
	s_addc_u32 s1, s35, 0
	s_add_i32 s17, s42, s45
	v_lshl_add_u64 v[138:139], s[0:1], 0, v[154:155]
	s_mov_b32 m0, s17
	s_nop 0
	global_load_lds_dwordx4 v[138:139], off
	v_lshl_add_u64 v[138:139], s[0:1], 0, v[128:129]
	s_add_i32 m0, s17, 0x2000
	s_nop 0
	global_load_lds_dwordx4 v[138:139], off
	s_waitcnt vmcnt(6)
	s_setprio 1
	s_barrier
	v_mfma_f32_16x16x32_bf16 v[52:55], v[208:211], v[164:167], v[52:55]
	v_mfma_f32_16x16x32_bf16 v[48:51], v[216:219], v[164:167], v[48:51]
	v_mfma_f32_16x16x32_bf16 v[36:39], v[208:211], v[184:187], v[36:39]
	v_mfma_f32_16x16x32_bf16 v[32:35], v[216:219], v[184:187], v[32:35]
	v_mfma_f32_16x16x32_bf16 v[20:23], v[208:211], v[192:195], v[20:23]
	v_mfma_f32_16x16x32_bf16 v[16:19], v[216:219], v[192:195], v[16:19]
	s_add_i32 s61, s61, 2
	v_mfma_f32_16x16x32_bf16 v[4:7], v[208:211], v[200:203], v[4:7]
	s_add_u32 s40, s40, 0x100
	v_mfma_f32_16x16x32_bf16 v[0:3], v[216:219], v[200:203], v[0:3]
	s_addc_u32 s41, s41, 0
	v_mfma_f32_16x16x32_bf16 v[52:55], v[212:215], v[168:171], v[52:55]
	s_add_u32 s58, s58, 0x100
	v_mfma_f32_16x16x32_bf16 v[48:51], v[220:223], v[168:171], v[48:51]
	s_addc_u32 s60, s60, 0
	v_mfma_f32_16x16x32_bf16 v[36:39], v[212:215], v[188:191], v[36:39]
	s_cmp_gt_u32 s61, 13
	v_mfma_f32_16x16x32_bf16 v[32:35], v[220:223], v[188:191], v[32:35]
	v_mfma_f32_16x16x32_bf16 v[20:23], v[212:215], v[196:199], v[20:23]
	v_mfma_f32_16x16x32_bf16 v[16:19], v[220:223], v[196:199], v[16:19]
	v_mfma_f32_16x16x32_bf16 v[4:7], v[212:215], v[204:207], v[4:7]
	v_mfma_f32_16x16x32_bf16 v[0:3], v[220:223], v[204:207], v[0:3]
	s_cbranch_scc1 .Lx_nobar_swiglu
	s_barrier
	s_setprio 0
	s_branch .LBB0_115

; __device__ __forceinline__ unsigned cvt_pk_bf16_nv(float lo, float hi) { return cvt_pk_bf16(lo, hi); }
;     __device__ __forceinline__ void operator()(const f32x4 (&acc)[2][2][4][2], const Unit& u, int wr, int wc, int fr, int fq) const {
;         const int row0 = u.pm * BM + wr * 64 + fr, col0 = u.pn * HALF + wc * 32 + 8 * fq;
; #pragma unroll
;         for (int ai = 0; ai < 2; ++ai)
; #pragma unroll
;             for (int m = 0; m < 4; ++m) { bf16_t* rowp = O + (size_t)(row0 + ai * HALF + m * 16) * ldc + col0;
;                 float h[8], ex[8];
; #pragma unroll
;                 for (int q = 0; q < 8; ++q) ex[q] = __builtin_amdgcn_exp2f(acc[ai][0][m][q >> 2][q & 3] * -1.4426950408889634f);
; #pragma unroll
;                 for (int q = 0; q < 8; ++q) ex[q] = __builtin_amdgcn_rcpf(1.0f + ex[q]);
; #pragma unroll
;                 for (int q = 0; q < 8; ++q) h[q] = (acc[ai][0][m][q >> 2][q & 3] * acc[ai][1][m][q >> 2][q & 3]) * ex[q];
;                 u32x4 w; w.x = cvt_pk_bf16_nv(h[0], h[1]); w.y = cvt_pk_bf16_nv(h[2], h[3]); w.z = cvt_pk_bf16_nv(h[4], h[5]); w.w = cvt_pk_bf16_nv(h[6], h[7]);
;                 *(u32x4*)rowp = w; }
.Lx_skip1_swiglu:
	v_mul_f32_e32 v148, 0xbfb8aa3b, v124
	v_mul_f32_e32 v149, 0xbfb8aa3b, v125
	v_mul_f32_e32 v150, 0xbfb8aa3b, v126
	v_mul_f32_e32 v151, 0xbfb8aa3b, v127
	v_mul_f32_e32 v152, 0xbfb8aa3b, v120
	v_mul_f32_e32 v153, 0xbfb8aa3b, v121
	v_exp_f32_e32 v148, v148
	v_exp_f32_e32 v149, v149
	v_exp_f32_e32 v150, v150
	v_exp_f32_e32 v151, v151
	v_exp_f32_e32 v152, v152
	v_exp_f32_e32 v153, v153
	v_mul_f32_e32 v160, 0xbfb8aa3b, v122
	v_mul_f32_e32 v161, 0xbfb8aa3b, v123
	v_exp_f32_e32 v160, v160
	v_exp_f32_e32 v161, v161
	v_add_f32_e32 v148, 1.0, v148
	v_add_f32_e32 v149, 1.0, v149
	v_add_f32_e32 v150, 1.0, v150
	v_add_f32_e32 v151, 1.0, v151
	v_add_f32_e32 v152, 1.0, v152
	v_add_f32_e32 v153, 1.0, v153
	v_rcp_f32_e32 v148, v148
	v_rcp_f32_e32 v149, v149
	v_rcp_f32_e32 v150, v150
	v_rcp_f32_e32 v151, v151
	v_rcp_f32_e32 v152, v152
	v_rcp_f32_e32 v153, v153
	v_add_f32_e32 v160, 1.0, v160
	v_add_f32_e32 v161, 1.0, v161
	v_rcp_f32_e32 v160, v160
	v_rcp_f32_e32 v161, v161
	v_lshl_or_b32 v140, s52, 7, v144
	v_pk_mul_f32 v[118:119], v[126:127], v[118:119]
	v_pk_mul_f32 v[116:117], v[124:125], v[116:117]
	v_pk_mul_f32 v[112:113], v[120:121], v[112:113]
	v_lshl_add_u32 v162, s38, 8, v142
	v_ashrrev_i32_e32 v141, 31, v140
	v_mov_b64_e32 v[138:139], s[22:23]
	v_pk_mul_f32 v[116:117], v[148:149], v[116:117]
	v_pk_mul_f32 v[118:119], v[150:151], v[118:119]
	v_pk_mul_f32 v[114:115], v[122:123], v[114:115]
	v_pk_mul_f32 v[112:113], v[152:153], v[112:113]
	v_mad_i64_i32 v[146:147], s[0:1], v162, s99, v[138:139]
	v_lshlrev_b64 v[140:141], 1, v[140:141]
	v_cvt_pk_bf16_f32 v116, v116, v117
	v_cvt_pk_bf16_f32 v117, v118, v119
	v_cvt_pk_bf16_f32 v118, v112, v113
	v_pk_mul_f32 v[112:113], v[160:161], v[114:115]
	v_lshl_add_u64 v[146:147], v[146:147], 0, v[140:141]
	v_cvt_pk_bf16_f32 v119, v112, v113
	global_store_dwordx4 v[146:147], v[116:119], off
	v_mul_f32_e32 v114, 0xbfb8aa3b, v108
	v_mul_f32_e32 v115, 0xbfb8aa3b, v109
	v_mul_f32_e32 v116, 0xbfb8aa3b, v110
	v_mul_f32_e32 v117, 0xbfb8aa3b, v111
	v_mul_f32_e32 v118, 0xbfb8aa3b, v104
	v_mul_f32_e32 v119, 0xbfb8aa3b, v105
	v_exp_f32_e32 v114, v114
	v_exp_f32_e32 v115, v115
	v_exp_f32_e32 v116, v116
	v_exp_f32_e32 v117, v117
	v_exp_f32_e32 v118, v118
	v_exp_f32_e32 v119, v119
	v_mul_f32_e32 v120, 0xbfb8aa3b, v106
	v_mul_f32_e32 v121, 0xbfb8aa3b, v107
	v_exp_f32_e32 v120, v120
	v_exp_f32_e32 v121, v121
	v_add_f32_e32 v114, 1.0, v114
	v_add_f32_e32 v115, 1.0, v115
	v_add_f32_e32 v116, 1.0, v116
	v_add_f32_e32 v117, 1.0, v117
	v_add_f32_e32 v118, 1.0, v118
	v_add_f32_e32 v119, 1.0, v119
	v_rcp_f32_e32 v114, v114
	v_rcp_f32_e32 v115, v115
	v_rcp_f32_e32 v116, v116
	v_rcp_f32_e32 v117, v117
	v_rcp_f32_e32 v118, v118
	v_rcp_f32_e32 v119, v119
	v_add_f32_e32 v120, 1.0, v120
	v_add_f32_e32 v121, 1.0, v121
	v_rcp_f32_e32 v120, v120
	v_rcp_f32_e32 v121, v121
	v_pk_mul_f32 v[102:103], v[110:111], v[102:103]
	v_pk_mul_f32 v[100:101], v[108:109], v[100:101]
	v_pk_mul_f32 v[96:97], v[104:105], v[96:97]
	v_or_b32_e32 v112, 16, v162
	v_pk_mul_f32 v[100:101], v[114:115], v[100:101]
	v_pk_mul_f32 v[102:103], v[116:117], v[102:103]
	v_pk_mul_f32 v[98:99], v[106:107], v[98:99]
	v_pk_mul_f32 v[96:97], v[118:119], v[96:97]
	v_mad_i64_i32 v[112:113], s[0:1], v112, s99, v[138:139]
	v_cvt_pk_bf16_f32 v100, v100, v101
	v_cvt_pk_bf16_f32 v101, v102, v103
	v_cvt_pk_bf16_f32 v102, v96, v97
	v_pk_mul_f32 v[96:97], v[120:121], v[98:99]
	v_lshl_add_u64 v[112:113], v[112:113], 0, v[140:141]
	v_cvt_pk_bf16_f32 v103, v96, v97
	global_store_dwordx4 v[112:113], v[100:103], off
	v_mul_f32_e32 v98, 0xbfb8aa3b, v92
	v_mul_f32_e32 v99, 0xbfb8aa3b, v93
	v_mul_f32_e32 v100, 0xbfb8aa3b, v94
	v_mul_f32_e32 v101, 0xbfb8aa3b, v95
	v_mul_f32_e32 v102, 0xbfb8aa3b, v88
	v_mul_f32_e32 v103, 0xbfb8aa3b, v89
	v_exp_f32_e32 v98, v98
	v_exp_f32_e32 v99, v99
	v_exp_f32_e32 v100, v100
	v_exp_f32_e32 v101, v101
	v_exp_f32_e32 v102, v102
	v_exp_f32_e32 v103, v103
	v_mul_f32_e32 v104, 0xbfb8aa3b, v90
	v_mul_f32_e32 v105, 0xbfb8aa3b, v91
	v_exp_f32_e32 v104, v104
	v_exp_f32_e32 v105, v105
	v_add_f32_e32 v98, 1.0, v98
	v_add_f32_e32 v99, 1.0, v99
	v_add_f32_e32 v100, 1.0, v100
	v_add_f32_e32 v101, 1.0, v101
	v_add_f32_e32 v102, 1.0, v102
	v_add_f32_e32 v103, 1.0, v103
	v_rcp_f32_e32 v98, v98
	v_rcp_f32_e32 v99, v99
	v_rcp_f32_e32 v100, v100
	v_rcp_f32_e32 v101, v101
	v_rcp_f32_e32 v102, v102
	v_rcp_f32_e32 v103, v103
	v_add_f32_e32 v104, 1.0, v104
	v_add_f32_e32 v105, 1.0, v105
	v_rcp_f32_e32 v104, v104
	v_rcp_f32_e32 v105, v105
	v_pk_mul_f32 v[86:87], v[94:95], v[86:87]
	v_pk_mul_f32 v[84:85], v[92:93], v[84:85]
	v_pk_mul_f32 v[80:81], v[88:89], v[80:81]
	v_or_b32_e32 v96, 32, v162
	v_pk_mul_f32 v[84:85], v[98:99], v[84:85]
	v_pk_mul_f32 v[86:87], v[100:101], v[86:87]
	v_pk_mul_f32 v[82:83], v[90:91], v[82:83]
	v_pk_mul_f32 v[80:81], v[102:103], v[80:81]
	v_mad_i64_i32 v[96:97], s[0:1], v96, s99, v[138:139]
	v_cvt_pk_bf16_f32 v84, v84, v85
	v_cvt_pk_bf16_f32 v85, v86, v87
	v_cvt_pk_bf16_f32 v86, v80, v81
	v_pk_mul_f32 v[80:81], v[104:105], v[82:83]
	v_lshl_add_u64 v[96:97], v[96:97], 0, v[140:141]
	v_cvt_pk_bf16_f32 v87, v80, v81
	global_store_dwordx4 v[96:97], v[84:87], off
	v_mul_f32_e32 v82, 0xbfb8aa3b, v76
	v_mul_f32_e32 v83, 0xbfb8aa3b, v77
	v_mul_f32_e32 v84, 0xbfb8aa3b, v78
	v_mul_f32_e32 v85, 0xbfb8aa3b, v79
	v_mul_f32_e32 v86, 0xbfb8aa3b, v72
	v_mul_f32_e32 v87, 0xbfb8aa3b, v73
	v_exp_f32_e32 v82, v82
	v_exp_f32_e32 v83, v83
	v_exp_f32_e32 v84, v84
	v_exp_f32_e32 v85, v85
	v_exp_f32_e32 v86, v86
	v_exp_f32_e32 v87, v87
	v_mul_f32_e32 v88, 0xbfb8aa3b, v74
	v_mul_f32_e32 v89, 0xbfb8aa3b, v75
	v_exp_f32_e32 v88, v88
	v_exp_f32_e32 v89, v89
	v_add_f32_e32 v82, 1.0, v82
; __device__ __forceinline__ unsigned cvt_pk_bf16_nv(float lo, float hi) { return cvt_pk_bf16(lo, hi); }
;     __device__ __forceinline__ void operator()(const f32x4 (&acc)[2][2][4][2], const Unit& u, int wr, int wc, int fr, int fq) const {
;     ...
;             for (int m = 0; m < 4; ++m) { bf16_t* rowp = O + (size_t)(row0 + ai * HALF + m * 16) * ldc + col0;
;                 float h[8], ex[8];
; #pragma unroll
;                 for (int q = 0; q < 8; ++q) ex[q] = __builtin_amdgcn_exp2f(acc[ai][0][m][q >> 2][q & 3] * -1.4426950408889634f);
; #pragma unroll
;                 for (int q = 0; q < 8; ++q) ex[q] = __builtin_amdgcn_rcpf(1.0f + ex[q]);
; #pragma unroll
;                 for (int q = 0; q < 8; ++q) h[q] = (acc[ai][0][m][q >> 2][q & 3] * acc[ai][1][m][q >> 2][q & 3]) * ex[q];
;                 u32x4 w; w.x = cvt_pk_bf16_nv(h[0], h[1]); w.y = cvt_pk_bf16_nv(h[2], h[3]); w.z = cvt_pk_bf16_nv(h[4], h[5]); w.w = cvt_pk_bf16_nv(h[6], h[7]);
;                 *(u32x4*)rowp = w; }
	v_add_f32_e32 v83, 1.0, v83
	v_add_f32_e32 v84, 1.0, v84
	v_add_f32_e32 v85, 1.0, v85
	v_add_f32_e32 v86, 1.0, v86
	v_add_f32_e32 v87, 1.0, v87
	v_rcp_f32_e32 v82, v82
	v_rcp_f32_e32 v83, v83
	v_rcp_f32_e32 v84, v84
	v_rcp_f32_e32 v85, v85
	v_rcp_f32_e32 v86, v86
	v_rcp_f32_e32 v87, v87
	v_add_f32_e32 v88, 1.0, v88
	v_add_f32_e32 v89, 1.0, v89
	v_rcp_f32_e32 v88, v88
	v_rcp_f32_e32 v89, v89
	v_pk_mul_f32 v[70:71], v[78:79], v[70:71]
	v_pk_mul_f32 v[68:69], v[76:77], v[68:69]
	v_pk_mul_f32 v[64:65], v[72:73], v[64:65]
	v_or_b32_e32 v80, 48, v162
	v_pk_mul_f32 v[68:69], v[82:83], v[68:69]
	v_pk_mul_f32 v[70:71], v[84:85], v[70:71]
	v_pk_mul_f32 v[66:67], v[74:75], v[66:67]
	v_pk_mul_f32 v[64:65], v[86:87], v[64:65]
	v_mad_i64_i32 v[80:81], s[0:1], v80, s99, v[138:139]
	v_cvt_pk_bf16_f32 v68, v68, v69
	v_cvt_pk_bf16_f32 v69, v70, v71
	v_cvt_pk_bf16_f32 v70, v64, v65
	v_pk_mul_f32 v[64:65], v[88:89], v[66:67]
	v_lshl_add_u64 v[80:81], v[80:81], 0, v[140:141]
	v_cvt_pk_bf16_f32 v71, v64, v65
	global_store_dwordx4 v[80:81], v[68:71], off
	v_mul_f32_e32 v66, 0xbfb8aa3b, v60
	v_mul_f32_e32 v67, 0xbfb8aa3b, v61
	v_mul_f32_e32 v68, 0xbfb8aa3b, v62
	v_mul_f32_e32 v69, 0xbfb8aa3b, v63
	v_mul_f32_e32 v70, 0xbfb8aa3b, v56
	v_mul_f32_e32 v71, 0xbfb8aa3b, v57
	v_exp_f32_e32 v66, v66
	v_exp_f32_e32 v67, v67
	v_exp_f32_e32 v68, v68
	v_exp_f32_e32 v69, v69
	v_exp_f32_e32 v70, v70
	v_exp_f32_e32 v71, v71
	v_mul_f32_e32 v72, 0xbfb8aa3b, v58
	v_mul_f32_e32 v73, 0xbfb8aa3b, v59
	v_exp_f32_e32 v72, v72
	v_exp_f32_e32 v73, v73
	v_add_f32_e32 v66, 1.0, v66
	v_add_f32_e32 v67, 1.0, v67
	v_add_f32_e32 v68, 1.0, v68
	v_add_f32_e32 v69, 1.0, v69
	v_add_f32_e32 v70, 1.0, v70
	v_add_f32_e32 v71, 1.0, v71
	v_rcp_f32_e32 v66, v66
	v_rcp_f32_e32 v67, v67
	v_rcp_f32_e32 v68, v68
	v_rcp_f32_e32 v69, v69
	v_rcp_f32_e32 v70, v70
	v_rcp_f32_e32 v71, v71
	v_add_f32_e32 v72, 1.0, v72
	v_add_f32_e32 v73, 1.0, v73
	v_rcp_f32_e32 v72, v72
	v_rcp_f32_e32 v73, v73
	v_pk_mul_f32 v[54:55], v[62:63], v[54:55]
	v_pk_mul_f32 v[52:53], v[60:61], v[52:53]
	v_pk_mul_f32 v[48:49], v[56:57], v[48:49]
	v_add_u32_e32 v64, 0x80, v162
	v_pk_mul_f32 v[52:53], v[66:67], v[52:53]
	v_pk_mul_f32 v[54:55], v[68:69], v[54:55]
	v_pk_mul_f32 v[50:51], v[58:59], v[50:51]
	v_pk_mul_f32 v[48:49], v[70:71], v[48:49]
	v_mad_i64_i32 v[64:65], s[0:1], v64, s99, v[138:139]
	v_cvt_pk_bf16_f32 v52, v52, v53
	v_cvt_pk_bf16_f32 v53, v54, v55
	v_cvt_pk_bf16_f32 v54, v48, v49
	v_pk_mul_f32 v[48:49], v[72:73], v[50:51]
	v_lshl_add_u64 v[64:65], v[64:65], 0, v[140:141]
	v_cvt_pk_bf16_f32 v55, v48, v49
	global_store_dwordx4 v[64:65], v[52:55], off
	v_mul_f32_e32 v50, 0xbfb8aa3b, v44
	v_mul_f32_e32 v51, 0xbfb8aa3b, v45
	v_mul_f32_e32 v52, 0xbfb8aa3b, v46
	v_mul_f32_e32 v53, 0xbfb8aa3b, v47
	v_mul_f32_e32 v54, 0xbfb8aa3b, v40
	v_mul_f32_e32 v55, 0xbfb8aa3b, v41
	v_exp_f32_e32 v50, v50
	v_exp_f32_e32 v51, v51
	v_exp_f32_e32 v52, v52
	v_exp_f32_e32 v53, v53
	v_exp_f32_e32 v54, v54
	v_exp_f32_e32 v55, v55
	v_mul_f32_e32 v56, 0xbfb8aa3b, v42
	v_mul_f32_e32 v57, 0xbfb8aa3b, v43
	v_exp_f32_e32 v56, v56
	v_exp_f32_e32 v57, v57
	v_add_f32_e32 v50, 1.0, v50
	v_add_f32_e32 v51, 1.0, v51
	v_add_f32_e32 v52, 1.0, v52
	v_add_f32_e32 v53, 1.0, v53
	v_add_f32_e32 v54, 1.0, v54
	v_add_f32_e32 v55, 1.0, v55
	v_rcp_f32_e32 v50, v50
	v_rcp_f32_e32 v51, v51
	v_rcp_f32_e32 v52, v52
	v_rcp_f32_e32 v53, v53
	v_rcp_f32_e32 v54, v54
	v_rcp_f32_e32 v55, v55
	v_add_f32_e32 v56, 1.0, v56
	v_add_f32_e32 v57, 1.0, v57
	v_rcp_f32_e32 v56, v56
	v_rcp_f32_e32 v57, v57
	v_pk_mul_f32 v[38:39], v[46:47], v[38:39]
	v_pk_mul_f32 v[36:37], v[44:45], v[36:37]
	v_pk_mul_f32 v[32:33], v[40:41], v[32:33]
	v_add_u32_e32 v48, 0x90, v162
	v_pk_mul_f32 v[36:37], v[50:51], v[36:37]
	v_pk_mul_f32 v[38:39], v[52:53], v[38:39]
	v_pk_mul_f32 v[34:35], v[42:43], v[34:35]
; __device__ __forceinline__ unsigned cvt_pk_bf16_nv(float lo, float hi) { return cvt_pk_bf16(lo, hi); }
;     __device__ __forceinline__ void operator()(const f32x4 (&acc)[2][2][4][2], const Unit& u, int wr, int wc, int fr, int fq) const {
;     ...
;             for (int m = 0; m < 4; ++m) { bf16_t* rowp = O + (size_t)(row0 + ai * HALF + m * 16) * ldc + col0;
;                 float h[8], ex[8];
; #pragma unroll
;                 for (int q = 0; q < 8; ++q) ex[q] = __builtin_amdgcn_exp2f(acc[ai][0][m][q >> 2][q & 3] * -1.4426950408889634f);
; #pragma unroll
;                 for (int q = 0; q < 8; ++q) ex[q] = __builtin_amdgcn_rcpf(1.0f + ex[q]);
; #pragma unroll
;                 for (int q = 0; q < 8; ++q) h[q] = (acc[ai][0][m][q >> 2][q & 3] * acc[ai][1][m][q >> 2][q & 3]) * ex[q];
;                 u32x4 w; w.x = cvt_pk_bf16_nv(h[0], h[1]); w.y = cvt_pk_bf16_nv(h[2], h[3]); w.z = cvt_pk_bf16_nv(h[4], h[5]); w.w = cvt_pk_bf16_nv(h[6], h[7]);
;                 *(u32x4*)rowp = w; }
; template <class Epi, class Sched>
; __device__ __forceinline__ void gemm_phase(LAS unsigned char* lds, const Gemm g, const Sched& S, const Epi& E, int tid) {
;     ...
;         E(acc, cur, wr, wc, fr, fq);
;         if (!has_next) break;
; #pragma unroll
;         for (int a = 0; a < 2; ++a)
; #pragma unroll
;             for (int b = 0; b < 2; ++b)
; #pragma unroll
;                 for (int m = 0; m < 4; ++m)
; #pragma unroll
;                     for (int n = 0; n < 2; ++n) acc[a][b][m][n] = (f32x4){0.f, 0.f, 0.f, 0.f};
;         cur = nxt; cA = nA; cB = nB; ++ui;
	v_pk_mul_f32 v[32:33], v[54:55], v[32:33]
	v_mad_i64_i32 v[48:49], s[0:1], v48, s99, v[138:139]
	v_cvt_pk_bf16_f32 v36, v36, v37
	v_cvt_pk_bf16_f32 v37, v38, v39
	v_cvt_pk_bf16_f32 v38, v32, v33
	v_pk_mul_f32 v[32:33], v[56:57], v[34:35]
	v_lshl_add_u64 v[48:49], v[48:49], 0, v[140:141]
	v_cvt_pk_bf16_f32 v39, v32, v33
	global_store_dwordx4 v[48:49], v[36:39], off
	v_mul_f32_e32 v34, 0xbfb8aa3b, v28
	v_mul_f32_e32 v35, 0xbfb8aa3b, v29
	v_mul_f32_e32 v36, 0xbfb8aa3b, v30
	v_mul_f32_e32 v37, 0xbfb8aa3b, v31
	v_mul_f32_e32 v38, 0xbfb8aa3b, v24
	v_mul_f32_e32 v39, 0xbfb8aa3b, v25
	v_exp_f32_e32 v34, v34
	v_exp_f32_e32 v35, v35
	v_exp_f32_e32 v36, v36
	v_exp_f32_e32 v37, v37
	v_exp_f32_e32 v38, v38
	v_exp_f32_e32 v39, v39
	v_mul_f32_e32 v40, 0xbfb8aa3b, v26
	v_mul_f32_e32 v41, 0xbfb8aa3b, v27
	v_exp_f32_e32 v40, v40
	v_exp_f32_e32 v41, v41
	v_add_f32_e32 v34, 1.0, v34
	v_add_f32_e32 v35, 1.0, v35
	v_add_f32_e32 v36, 1.0, v36
	v_add_f32_e32 v37, 1.0, v37
	v_add_f32_e32 v38, 1.0, v38
	v_add_f32_e32 v39, 1.0, v39
	v_rcp_f32_e32 v34, v34
	v_rcp_f32_e32 v35, v35
	v_rcp_f32_e32 v36, v36
	v_rcp_f32_e32 v37, v37
	v_rcp_f32_e32 v38, v38
	v_rcp_f32_e32 v39, v39
	v_add_f32_e32 v40, 1.0, v40
	v_add_f32_e32 v41, 1.0, v41
	v_rcp_f32_e32 v40, v40
	v_rcp_f32_e32 v41, v41
	v_pk_mul_f32 v[22:23], v[30:31], v[22:23]
	v_pk_mul_f32 v[20:21], v[28:29], v[20:21]
	v_pk_mul_f32 v[16:17], v[24:25], v[16:17]
	v_add_u32_e32 v32, 0xa0, v162
	v_pk_mul_f32 v[20:21], v[34:35], v[20:21]
	v_pk_mul_f32 v[22:23], v[36:37], v[22:23]
	v_pk_mul_f32 v[18:19], v[26:27], v[18:19]
	v_pk_mul_f32 v[16:17], v[38:39], v[16:17]
	v_mad_i64_i32 v[32:33], s[0:1], v32, s99, v[138:139]
	v_cvt_pk_bf16_f32 v20, v20, v21
	v_cvt_pk_bf16_f32 v21, v22, v23
	v_cvt_pk_bf16_f32 v22, v16, v17
	v_pk_mul_f32 v[16:17], v[40:41], v[18:19]
	v_lshl_add_u64 v[32:33], v[32:33], 0, v[140:141]
	v_cvt_pk_bf16_f32 v23, v16, v17
	global_store_dwordx4 v[32:33], v[20:23], off
	v_mul_f32_e32 v18, 0xbfb8aa3b, v12
	v_mul_f32_e32 v19, 0xbfb8aa3b, v13
	v_mul_f32_e32 v20, 0xbfb8aa3b, v14
	v_mul_f32_e32 v21, 0xbfb8aa3b, v15
	v_mul_f32_e32 v22, 0xbfb8aa3b, v8
	v_mul_f32_e32 v23, 0xbfb8aa3b, v9
	v_exp_f32_e32 v18, v18
	v_exp_f32_e32 v19, v19
	v_exp_f32_e32 v20, v20
	v_exp_f32_e32 v21, v21
	v_exp_f32_e32 v22, v22
	v_exp_f32_e32 v23, v23
	v_mul_f32_e32 v24, 0xbfb8aa3b, v10
	v_mul_f32_e32 v25, 0xbfb8aa3b, v11
	v_exp_f32_e32 v24, v24
	v_exp_f32_e32 v25, v25
	v_add_f32_e32 v18, 1.0, v18
	v_add_f32_e32 v19, 1.0, v19
	v_add_f32_e32 v20, 1.0, v20
	v_add_f32_e32 v21, 1.0, v21
	v_add_f32_e32 v22, 1.0, v22
	v_add_f32_e32 v23, 1.0, v23
	v_rcp_f32_e32 v18, v18
	v_rcp_f32_e32 v19, v19
	v_rcp_f32_e32 v20, v20
	v_rcp_f32_e32 v21, v21
	v_rcp_f32_e32 v22, v22
	v_rcp_f32_e32 v23, v23
	v_add_f32_e32 v24, 1.0, v24
	v_add_f32_e32 v25, 1.0, v25
	v_rcp_f32_e32 v24, v24
	v_rcp_f32_e32 v25, v25
	v_pk_mul_f32 v[6:7], v[14:15], v[6:7]
	v_pk_mul_f32 v[4:5], v[12:13], v[4:5]
	v_pk_mul_f32 v[0:1], v[8:9], v[0:1]
	v_add_u32_e32 v16, 0xb0, v162
	v_pk_mul_f32 v[4:5], v[18:19], v[4:5]
	v_pk_mul_f32 v[6:7], v[20:21], v[6:7]
	v_pk_mul_f32 v[2:3], v[10:11], v[2:3]
	v_pk_mul_f32 v[0:1], v[22:23], v[0:1]
	v_mad_i64_i32 v[16:17], s[0:1], v16, s99, v[138:139]
	v_cvt_pk_bf16_f32 v4, v4, v5
	v_cvt_pk_bf16_f32 v5, v6, v7
	v_cvt_pk_bf16_f32 v6, v0, v1
	v_pk_mul_f32 v[0:1], v[24:25], v[2:3]
	v_lshl_add_u64 v[16:17], v[16:17], 0, v[140:141]
	v_cvt_pk_bf16_f32 v7, v0, v1
	s_and_b64 vcc, exec, s[36:37]
	s_mov_b32 s52, s14
	s_mov_b32 s38, s24
	s_mov_b64 s[42:43], s[30:31]
	s_mov_b64 s[40:41], s[28:29]
	global_store_dwordx4 v[16:17], v[4:7], off
	s_cmp_lg_u32 s100, 0
	s_cbranch_scc0 .Lx_skip2_swiglu
	s_barrier
.Lx_skip2_swiglu:
	s_cbranch_vccz .LBB0_112
	s_waitcnt vmcnt(0)
	s_cmpk_gt_u32 s18, 0xff
	s_cbranch_scc1 .LBB0_119
	s_barrier
